# K64 line-shaped GEMM loops (G1/G3/G4) + dprep LoRA weight prefetch + RWKV scan steps re-emitted with interleaved reductions (bit-identical)
# speedup vs baseline: 1.0467x; 1.0146x over previous
.LBB0_285:
	v_lshlrev_b64 v[30:31], 2, v[0:1]
	v_lshl_add_u64 v[34:35], s[4:5], 0, v[30:31]
	v_lshl_add_u64 v[36:37], s[6:7], 0, v[30:31]
	global_load_dword v23, v[34:35], off
	global_load_dword v19, v[34:35], off offset:1024
	global_load_dword v1, v[34:35], off offset:2048
	global_load_dword v115, v[36:37], off
	global_load_dword v114, v[36:37], off offset:1024
	global_load_dword v21, v[36:37], off offset:2048
	v_mov_b32_e32 v36, 0
	v_lshl_add_u64 v[108:109], s[8:9], 0, v[30:31]
	v_lshl_add_u64 v[110:111], s[10:11], 0, v[30:31]
	s_mov_b64 s[12:13], 0
	s_mov_b32 s14, 16
	v_lshl_add_u64 v[166:167], v[108:109], 0, s[12:13]
	s_mov_b32 s15, 0x10000
	v_add_co_u32_e32 v168, vcc, s15, v166
	v_lshl_add_u64 v[170:171], v[110:111], 0, s[12:13]
	s_nop 0
	v_addc_co_u32_e32 v169, vcc, 0, v167, vcc
	global_load_dword v172, v[166:167], off
	global_load_dword v173, v[168:169], off
	global_load_dword v176, v[170:171], off
	global_load_dword v180, v[166:167], off offset:1024
	global_load_dword v181, v[168:169], off offset:1024
	global_load_dword v182, v[170:171], off offset:1024
	v_mov_b32_e32 v37, v36
	v_mov_b32_e32 v106, v36
	v_mov_b32_e32 v107, v36
	v_mov_b32_e32 v98, v36
	v_mov_b32_e32 v99, v36
	v_mov_b32_e32 v88, v36
	v_mov_b32_e32 v89, v36
	v_mov_b32_e32 v78, v36
	v_mov_b32_e32 v79, v36
	v_mov_b32_e32 v68, v36
	v_mov_b32_e32 v69, v36
	v_mov_b32_e32 v56, v36
	v_mov_b32_e32 v57, v36
	v_mov_b32_e32 v46, v36
	v_mov_b32_e32 v47, v36
	v_mov_b32_e32 v34, v36
	v_mov_b32_e32 v35, v36
	v_mov_b32_e32 v104, v36
	v_mov_b32_e32 v105, v36
	v_mov_b32_e32 v96, v36
	v_mov_b32_e32 v97, v36
	v_mov_b32_e32 v86, v36
	v_mov_b32_e32 v87, v36
	v_mov_b32_e32 v76, v36
	v_mov_b32_e32 v77, v36
	v_mov_b32_e32 v64, v36
	v_mov_b32_e32 v65, v36
	v_mov_b32_e32 v54, v36
	v_mov_b32_e32 v55, v36
	v_mov_b32_e32 v44, v36
	v_mov_b32_e32 v45, v36
	v_mov_b32_e32 v30, v36
	v_mov_b32_e32 v31, v36
	v_mov_b32_e32 v42, v36
	v_mov_b32_e32 v43, v36
	v_mov_b32_e32 v52, v36
	v_mov_b32_e32 v53, v36
	v_mov_b32_e32 v62, v36
	v_mov_b32_e32 v63, v36
	v_mov_b32_e32 v72, v36
	v_mov_b32_e32 v73, v36
	v_mov_b32_e32 v84, v36
	v_mov_b32_e32 v85, v36
	v_mov_b32_e32 v94, v36
	v_mov_b32_e32 v95, v36
	v_mov_b32_e32 v102, v36
	v_mov_b32_e32 v103, v36
.LBB0_286:
	s_waitcnt vmcnt(0)
	v_mov_b32_e32 v158, v172
	v_mov_b32_e32 v162, v173
	v_mov_b32_e32 v164, v176
	v_mov_b32_e32 v184, v180
	v_mov_b32_e32 v186, v181
	v_mov_b32_e32 v188, v182
	v_mov_b32_e32 v131, s14
	ds_read_b128 v[132:135], v131
	ds_read_b128 v[136:139], v131 offset:16
	ds_read_b128 v[140:143], v131 offset:32
	ds_read_b128 v[144:147], v131 offset:48
	ds_read_b128 v[148:151], v131 offset:4096
	ds_read_b128 v[152:155], v131 offset:8192
	s_add_u32 s12, s12, 0x800
	s_addc_u32 s13, s13, 0
	s_addk_i32 s14, 0x80
	s_cmp_lg_u32 s12, 0x10000
	s_cbranch_scc0 .Ldp_nopf
	v_lshl_add_u64 v[166:167], v[108:109], 0, s[12:13]
	s_mov_b32 s15, 0x10000
	v_add_co_u32_e32 v168, vcc, s15, v166
	v_lshl_add_u64 v[170:171], v[110:111], 0, s[12:13]
	s_nop 0
	v_addc_co_u32_e32 v169, vcc, 0, v167, vcc
	global_load_dword v172, v[166:167], off
	global_load_dword v173, v[168:169], off
	global_load_dword v176, v[170:171], off
	global_load_dword v180, v[166:167], off offset:1024
	global_load_dword v181, v[168:169], off offset:1024
	global_load_dword v182, v[170:171], off offset:1024
.Ldp_nopf:
	s_waitcnt lgkmcnt(2)
	v_pk_fma_f32 v[46:47], v[158:159], v[144:145], v[46:47] op_sel_hi:[0,1,1]
	s_waitcnt lgkmcnt(1)
	v_pk_fma_f32 v[148:149], v[162:163], v[148:149], v[104:105] op_sel_hi:[0,1,1]
	s_waitcnt lgkmcnt(0)
	v_pk_fma_f32 v[152:153], v[164:165], v[152:153], v[102:103] op_sel_hi:[0,1,1]
	v_pk_fma_f32 v[150:151], v[162:163], v[150:151], v[96:97] op_sel_hi:[0,1,1]
	v_pk_fma_f32 v[154:155], v[164:165], v[154:155], v[94:95] op_sel_hi:[0,1,1]
	ds_read_b128 v[94:97], v131 offset:4112
	ds_read_b128 v[102:105], v131 offset:8208
	v_pk_fma_f32 v[36:37], v[158:159], v[146:147], v[36:37] op_sel_hi:[0,1,1]
	v_pk_fma_f32 v[106:107], v[158:159], v[132:133], v[106:107] op_sel_hi:[0,1,1]
	v_pk_fma_f32 v[98:99], v[158:159], v[134:135], v[98:99] op_sel_hi:[0,1,1]
	s_waitcnt lgkmcnt(1)
	v_pk_fma_f32 v[86:87], v[162:163], v[94:95], v[86:87] op_sel_hi:[0,1,1]
	s_waitcnt lgkmcnt(0)
	v_pk_fma_f32 v[84:85], v[164:165], v[102:103], v[84:85] op_sel_hi:[0,1,1]
	v_pk_fma_f32 v[76:77], v[162:163], v[96:97], v[76:77] op_sel_hi:[0,1,1]
	v_pk_fma_f32 v[72:73], v[164:165], v[104:105], v[72:73] op_sel_hi:[0,1,1]
	ds_read_b128 v[94:97], v131 offset:4128
	ds_read_b128 v[102:105], v131 offset:8224
	v_pk_fma_f32 v[88:89], v[158:159], v[136:137], v[88:89] op_sel_hi:[0,1,1]
	v_pk_fma_f32 v[78:79], v[158:159], v[138:139], v[78:79] op_sel_hi:[0,1,1]
	v_pk_fma_f32 v[68:69], v[158:159], v[140:141], v[68:69] op_sel_hi:[0,1,1]
	s_waitcnt lgkmcnt(1)
	v_pk_fma_f32 v[64:65], v[162:163], v[94:95], v[64:65] op_sel_hi:[0,1,1]
	s_waitcnt lgkmcnt(0)
	v_pk_fma_f32 v[62:63], v[164:165], v[102:103], v[62:63] op_sel_hi:[0,1,1]
	v_pk_fma_f32 v[54:55], v[162:163], v[96:97], v[54:55] op_sel_hi:[0,1,1]
	v_pk_fma_f32 v[52:53], v[164:165], v[104:105], v[52:53] op_sel_hi:[0,1,1]
	ds_read_b128 v[94:97], v131 offset:4144
	ds_read_b128 v[102:105], v131 offset:8240
	v_pk_fma_f32 v[56:57], v[158:159], v[142:143], v[56:57] op_sel_hi:[0,1,1]
	s_waitcnt lgkmcnt(1)
	v_pk_fma_f32 v[44:45], v[162:163], v[94:95], v[44:45] op_sel_hi:[0,1,1]
	v_pk_fma_f32 v[34:35], v[162:163], v[96:97], v[34:35] op_sel_hi:[0,1,1]
	ds_read_b128 v[94:97], v131 offset:64
	ds_read_b128 v[132:135], v131 offset:4160
	ds_read_b128 v[136:139], v131 offset:8256
	s_waitcnt lgkmcnt(3)
	v_pk_fma_f32 v[42:43], v[164:165], v[102:103], v[42:43] op_sel_hi:[0,1,1]
	v_pk_fma_f32 v[30:31], v[164:165], v[104:105], v[30:31] op_sel_hi:[0,1,1]
	s_waitcnt lgkmcnt(2)
	v_pk_fma_f32 v[106:107], v[184:185], v[94:95], v[106:107] op_sel_hi:[0,1,1]
	s_waitcnt lgkmcnt(1)
	v_pk_fma_f32 v[104:105], v[186:187], v[132:133], v[148:149] op_sel_hi:[0,1,1]
	s_waitcnt lgkmcnt(0)
	v_pk_fma_f32 v[102:103], v[188:189], v[136:137], v[152:153] op_sel_hi:[0,1,1]
	v_pk_fma_f32 v[98:99], v[184:185], v[96:97], v[98:99] op_sel_hi:[0,1,1]
	v_pk_fma_f32 v[96:97], v[186:187], v[134:135], v[150:151] op_sel_hi:[0,1,1]
	v_pk_fma_f32 v[94:95], v[188:189], v[138:139], v[154:155] op_sel_hi:[0,1,1]
	ds_read_b128 v[132:135], v131 offset:80
	ds_read_b128 v[136:139], v131 offset:4176
	ds_read_b128 v[140:143], v131 offset:8272
	s_waitcnt lgkmcnt(2)
	v_pk_fma_f32 v[88:89], v[184:185], v[132:133], v[88:89] op_sel_hi:[0,1,1]
	s_waitcnt lgkmcnt(1)
	v_pk_fma_f32 v[86:87], v[186:187], v[136:137], v[86:87] op_sel_hi:[0,1,1]
	s_waitcnt lgkmcnt(0)
	v_pk_fma_f32 v[84:85], v[188:189], v[140:141], v[84:85] op_sel_hi:[0,1,1]
	v_pk_fma_f32 v[78:79], v[184:185], v[134:135], v[78:79] op_sel_hi:[0,1,1]
	v_pk_fma_f32 v[76:77], v[186:187], v[138:139], v[76:77] op_sel_hi:[0,1,1]
	v_pk_fma_f32 v[72:73], v[188:189], v[142:143], v[72:73] op_sel_hi:[0,1,1]
	ds_read_b128 v[132:135], v131 offset:96
	ds_read_b128 v[136:139], v131 offset:4192
	ds_read_b128 v[140:143], v131 offset:8288
	s_waitcnt lgkmcnt(2)
	v_pk_fma_f32 v[68:69], v[184:185], v[132:133], v[68:69] op_sel_hi:[0,1,1]
	s_waitcnt lgkmcnt(1)
	v_pk_fma_f32 v[64:65], v[186:187], v[136:137], v[64:65] op_sel_hi:[0,1,1]
	s_waitcnt lgkmcnt(0)
	v_pk_fma_f32 v[62:63], v[188:189], v[140:141], v[62:63] op_sel_hi:[0,1,1]
	v_pk_fma_f32 v[56:57], v[184:185], v[134:135], v[56:57] op_sel_hi:[0,1,1]
	v_pk_fma_f32 v[54:55], v[186:187], v[138:139], v[54:55] op_sel_hi:[0,1,1]
	v_pk_fma_f32 v[52:53], v[188:189], v[142:143], v[52:53] op_sel_hi:[0,1,1]
	ds_read_b128 v[132:135], v131 offset:112
	ds_read_b128 v[136:139], v131 offset:4208
	ds_read_b128 v[140:143], v131 offset:8304
	s_waitcnt lgkmcnt(2)
	v_pk_fma_f32 v[46:47], v[184:185], v[132:133], v[46:47] op_sel_hi:[0,1,1]
	s_waitcnt lgkmcnt(1)
	v_pk_fma_f32 v[44:45], v[186:187], v[136:137], v[44:45] op_sel_hi:[0,1,1]
	s_waitcnt lgkmcnt(0)
	v_pk_fma_f32 v[42:43], v[188:189], v[140:141], v[42:43] op_sel_hi:[0,1,1]
	v_pk_fma_f32 v[36:37], v[184:185], v[134:135], v[36:37] op_sel_hi:[0,1,1]
	v_pk_fma_f32 v[34:35], v[186:187], v[138:139], v[34:35] op_sel_hi:[0,1,1]
	v_pk_fma_f32 v[30:31], v[188:189], v[142:143], v[30:31] op_sel_hi:[0,1,1]
	s_cbranch_scc1 .LBB0_286
	v_add_f32_e32 v106, v11, v106
	v_mul_f32_e32 v106, 0xbfb8aa3b, v106
	v_exp_f32_e32 v106, v106
	v_pk_add_f32 v[100:101], v[100:101], v[92:93] neg_lo:[0,1] neg_hi:[0,1]
	v_mov_b32_e32 v112, v93
	v_fmac_f32_e32 v112, v101, v23
	v_mov_b32_e32 v101, v92
	v_pk_add_f32 v[110:111], v[90:91], v[92:93] neg_lo:[0,1] neg_hi:[0,1]
	v_fmac_f32_e32 v101, v100, v19
	v_sub_f32_e32 v100, v130, v129
	v_fmac_f32_e32 v101, v110, v114
	v_fma_f32 v100, v100, v1, v129
	v_sub_f32_e32 v110, v128, v129
	v_add_f32_e32 v106, 1.0, v106
	v_fmac_f32_e32 v100, v110, v21
	v_div_scale_f32 v110, s[12:13], v106, v106, s39
	v_fmac_f32_e32 v112, v111, v115
	v_rcp_f32_e32 v111, v110
	v_add_f32_e32 v104, v9, v104
	v_mul_f32_e32 v104, 0xbfb8aa3b, v104
	v_exp_f32_e32 v104, v104
	v_fma_f32 v113, -v110, v111, 1.0
	v_fmac_f32_e32 v111, v113, v111
	v_div_scale_f32 v113, vcc, s39, v106, s39
	v_mul_f32_e32 v130, v113, v111
	v_fma_f32 v131, -v110, v130, v113
	v_fmac_f32_e32 v130, v131, v111
	v_fma_f32 v110, -v110, v130, v113
	v_div_fmas_f32 v110, v110, v111, v130
	v_add_f32_e32 v104, 1.0, v104
	v_div_fixup_f32 v106, v110, v106, s39
	v_div_scale_f32 v110, s[12:13], v104, v104, s39
	v_rcp_f32_e32 v111, v110
	v_add_f32_e32 v102, v7, v102
	v_mul_f32_e32 v102, 0xbfb8aa3b, v102
	v_exp_f32_e32 v102, v102
	v_fma_f32 v113, -v110, v111, 1.0
	v_fmac_f32_e32 v111, v113, v111
	v_div_scale_f32 v113, vcc, s39, v104, s39
	v_mul_f32_e32 v130, v113, v111
	v_fma_f32 v131, -v110, v130, v113
	v_fmac_f32_e32 v130, v131, v111
	v_fma_f32 v110, -v110, v130, v113
	v_div_fmas_f32 v110, v110, v111, v130
	v_add_f32_e32 v102, 1.0, v102
	v_div_fixup_f32 v104, v110, v104, s39
	v_div_scale_f32 v110, s[12:13], v102, v102, 1.0
	v_rcp_f32_e32 v111, v110
	v_mul_f32_e32 v106, 0x3fb8aa3b, v106
	v_exp_f32_e32 v106, v106
	v_mul_f32_e32 v104, 0x3fb8aa3b, v104
	v_fma_f32 v113, -v110, v111, 1.0
	v_fmac_f32_e32 v111, v113, v111
	v_div_scale_f32 v113, vcc, 1.0, v102, 1.0
	v_mul_f32_e32 v130, v113, v111
	v_fma_f32 v131, -v110, v130, v113
	v_fmac_f32_e32 v130, v131, v111
	v_fma_f32 v110, -v110, v130, v113
	v_div_fmas_f32 v110, v110, v111, v130
	v_div_fixup_f32 v102, v110, v102, 1.0
	v_mul_f32_e32 v110, v5, v101
	v_mul_f32_e32 v111, v110, v110
	v_exp_f32_e32 v104, v104
	v_lshl_add_u32 v109, v0, 1, 16
	v_mov_b32_dpp v111, v111 quad_perm:[1,0,3,2] row_mask:0xf bank_mask:0xf bound_ctrl:1
	v_fmac_f32_e32 v111, v110, v110
	v_cvt_pk_bf16_f32 v100, v100, s0
	ds_write_b16 v109, v100 offset:28672
	v_add_f32_dpp v111, v111, v111 quad_perm:[2,3,0,1] row_mask:0xf bank_mask:0xf bound_ctrl:1
	v_sub_f32_e32 v106, 1.0, v106
	v_sub_f32_e32 v104, 1.0, v104
	v_add_f32_dpp v111, v111, v111 row_half_mirror row_mask:0xf bank_mask:0xf bound_ctrl:1
	v_pk_add_f32 v[92:93], v[92:93], v[90:91] neg_lo:[0,1] neg_hi:[0,1]
	v_add_f32_e32 v103, v7, v103
	v_add_f32_dpp v111, v111, v111 row_mirror row_mask:0xf bank_mask:0xf bound_ctrl:1
	v_mul_f32_e32 v103, 0xbfb8aa3b, v103
	v_readlane_b32 s13, v111, 16
	v_readlane_b32 s12, v111, 0
	v_exp_f32_e32 v103, v103
	v_mov_b32_e32 v113, s13
	v_readlane_b32 s13, v111, 48
	v_add_f32_e32 v113, s12, v113
	v_readlane_b32 s12, v111, 32
	v_mov_b32_e32 v111, s13
	v_add_f32_e32 v103, 1.0, v103
	v_add_f32_e32 v111, s12, v111
	v_add_f32_e32 v111, v113, v111
	v_max_f32_e32 v111, 0x179abe15, v111
	v_rsq_f32_e32 v111, v111
	v_add_f32_e32 v94, v7, v94
	v_mul_f32_e32 v94, 0xbfb8aa3b, v94
	v_exp_f32_e32 v94, v94
	v_mul_f32_e32 v110, v110, v111
	v_add_f32_e32 v111, -1.0, v102
	v_mul_f32_e32 v102, v102, v110
	v_cvt_pk_bf16_f32 v100, -v110, s0
	v_fma_f32 v111, v3, v111, 1.0
	ds_write_b16 v109, v100 offset:36864
	v_cvt_pk_bf16_f32 v100, v102, s0
	v_mul_f32_e32 v101, v101, v111
	ds_write_b16 v109, v100 offset:45056
	v_cvt_pk_bf16_f32 v100, v106, s0
	v_mov_b32_e32 v102, v91
	v_cvt_pk_bf16_f32 v101, v101, s0
	ds_write_b16 v109, v100 offset:53248
	v_cvt_pk_bf16_f32 v100, v104, s0
	v_fmac_f32_e32 v102, v93, v23
	v_mov_b32_e32 v93, v90
	ds_write_b16 v109, v101 offset:20480
	ds_write_b16 v109, v100 offset:61440
	v_pk_add_f32 v[100:101], v[82:83], v[90:91] neg_lo:[0,1] neg_hi:[0,1]
	v_fmac_f32_e32 v93, v92, v19
	v_sub_f32_e32 v92, v129, v128
	v_fmac_f32_e32 v93, v100, v114
	v_fma_f32 v92, v92, v1, v128
	v_sub_f32_e32 v100, v127, v128
	v_fmac_f32_e32 v92, v100, v21
	v_add_f32_e32 v100, v11, v107
	v_mul_f32_e32 v100, 0xbfb8aa3b, v100
	v_exp_f32_e32 v100, v100
	v_fmac_f32_e32 v102, v101, v115
	v_cvt_pk_bf16_f32 v92, v92, s0
	ds_write_b16 v109, v92 offset:29184
	v_add_f32_e32 v100, 1.0, v100
	v_div_scale_f32 v101, s[12:13], v100, v100, s39
	v_rcp_f32_e32 v104, v101
	v_pk_add_f32 v[90:91], v[90:91], v[82:83] neg_lo:[0,1] neg_hi:[0,1]
	v_cvt_pk_bf16_f32 v102, v102, s0
	ds_write_b16 v109, v102 offset:12800
	v_fma_f32 v106, -v101, v104, 1.0
	v_fmac_f32_e32 v104, v106, v104
	v_div_scale_f32 v106, vcc, s39, v100, s39
	v_mul_f32_e32 v107, v106, v104
	v_fma_f32 v110, -v101, v107, v106
	v_fmac_f32_e32 v107, v110, v104
	v_fma_f32 v101, -v101, v107, v106
	v_div_fmas_f32 v101, v101, v104, v107
	v_div_fixup_f32 v100, v101, v100, s39
	v_add_f32_e32 v101, v9, v105
	v_mul_f32_e32 v101, 0xbfb8aa3b, v101
	v_exp_f32_e32 v101, v101
	v_mul_f32_e32 v100, 0x3fb8aa3b, v100
	v_exp_f32_e32 v100, v100
	v_add_f32_e32 v94, 1.0, v94
	v_add_f32_e32 v101, 1.0, v101
	v_div_scale_f32 v104, s[12:13], v101, v101, s39
	v_rcp_f32_e32 v105, v104
	v_sub_f32_e32 v100, 1.0, v100
	v_add_f32_e32 v84, v7, v84
	v_mul_f32_e32 v84, 0xbfb8aa3b, v84
	v_fma_f32 v106, -v104, v105, 1.0
	v_fmac_f32_e32 v105, v106, v105
	v_div_scale_f32 v106, vcc, s39, v101, s39
	v_mul_f32_e32 v107, v106, v105
	v_fma_f32 v110, -v104, v107, v106
	v_fmac_f32_e32 v107, v110, v105
	v_fma_f32 v104, -v104, v107, v106
	v_div_fmas_f32 v104, v104, v105, v107
	v_div_fixup_f32 v101, v104, v101, s39
	v_div_scale_f32 v104, s[12:13], v103, v103, 1.0
	v_rcp_f32_e32 v105, v104
	v_mul_f32_e32 v101, 0x3fb8aa3b, v101
	v_exp_f32_e32 v101, v101
	v_exp_f32_e32 v84, v84
	v_fma_f32 v106, -v104, v105, 1.0
	v_fmac_f32_e32 v105, v106, v105
	v_div_scale_f32 v106, vcc, 1.0, v103, 1.0
	v_mul_f32_e32 v107, v106, v105
	v_fma_f32 v110, -v104, v107, v106
	v_fmac_f32_e32 v107, v110, v105
	v_fma_f32 v104, -v104, v107, v106
	v_div_fmas_f32 v104, v104, v105, v107
	v_div_fixup_f32 v103, v104, v103, 1.0
	v_mul_f32_e32 v104, v5, v93
	v_mul_f32_e32 v105, v104, v104
	v_sub_f32_e32 v101, 1.0, v101
	v_add_f32_e32 v84, 1.0, v84
	v_mov_b32_dpp v105, v105 quad_perm:[1,0,3,2] row_mask:0xf bank_mask:0xf bound_ctrl:1
	v_fmac_f32_e32 v105, v104, v104
	v_add_f32_e32 v72, v7, v72
	v_mul_f32_e32 v72, 0xbfb8aa3b, v72
	v_add_f32_dpp v105, v105, v105 quad_perm:[2,3,0,1] row_mask:0xf bank_mask:0xf bound_ctrl:1
	v_exp_f32_e32 v72, v72
	v_add_f32_e32 v73, v7, v73
	v_add_f32_dpp v105, v105, v105 row_half_mirror row_mask:0xf bank_mask:0xf bound_ctrl:1
	v_mul_f32_e32 v73, 0xbfb8aa3b, v73
	v_add_f32_e32 v72, 1.0, v72
	v_add_f32_dpp v105, v105, v105 row_mirror row_mask:0xf bank_mask:0xf bound_ctrl:1
	v_exp_f32_e32 v73, v73
	v_readlane_b32 s13, v105, 16
	v_readlane_b32 s12, v105, 0
	v_add_f32_e32 v64, v9, v64
	v_mov_b32_e32 v106, s13
	v_readlane_b32 s13, v105, 48
	v_add_f32_e32 v106, s12, v106
	v_readlane_b32 s12, v105, 32
	v_mov_b32_e32 v105, s13
	v_add_f32_e32 v73, 1.0, v73
	v_add_f32_e32 v105, s12, v105
	v_add_f32_e32 v105, v106, v105
	v_max_f32_e32 v105, 0x179abe15, v105
	v_rsq_f32_e32 v105, v105
	v_mul_f32_e32 v64, 0xbfb8aa3b, v64
	v_exp_f32_e32 v64, v64
	v_add_f32_e32 v62, v7, v62
	v_mul_f32_e32 v104, v104, v105
	v_add_f32_e32 v105, -1.0, v103
	v_mul_f32_e32 v103, v103, v104
	v_cvt_pk_bf16_f32 v92, -v104, s0
	v_fma_f32 v105, v3, v105, 1.0
	ds_write_b16 v109, v92 offset:37376
	v_cvt_pk_bf16_f32 v92, v103, s0
	v_mul_f32_e32 v93, v93, v105
	ds_write_b16 v109, v92 offset:45568
	v_cvt_pk_bf16_f32 v92, v100, s0
	v_mov_b32_e32 v100, v83
	v_cvt_pk_bf16_f32 v93, v93, s0
	ds_write_b16 v109, v92 offset:53760
	v_cvt_pk_bf16_f32 v92, v101, s0
	v_fmac_f32_e32 v100, v91, v23
	v_mov_b32_e32 v91, v82
	ds_write_b16 v109, v93 offset:20992
	ds_write_b16 v109, v92 offset:61952
	v_pk_add_f32 v[92:93], v[80:81], v[82:83] neg_lo:[0,1] neg_hi:[0,1]
	v_fmac_f32_e32 v91, v90, v19
	v_sub_f32_e32 v90, v128, v127
	v_fmac_f32_e32 v91, v92, v114
	v_fma_f32 v90, v90, v1, v127
	v_sub_f32_e32 v92, v126, v127
	v_fmac_f32_e32 v90, v92, v21
	v_add_f32_e32 v92, v11, v98
	v_mul_f32_e32 v92, 0xbfb8aa3b, v92
	v_exp_f32_e32 v92, v92
	v_fmac_f32_e32 v100, v93, v115
	v_cvt_pk_bf16_f32 v90, v90, s0
	ds_write_b16 v109, v90 offset:29696
	v_add_f32_e32 v92, 1.0, v92
	v_div_scale_f32 v93, s[12:13], v92, v92, s39
	v_rcp_f32_e32 v98, v93
	v_pk_add_f32 v[82:83], v[82:83], v[80:81] neg_lo:[0,1] neg_hi:[0,1]
	v_add_f32_e32 v64, 1.0, v64
	v_mul_f32_e32 v62, 0xbfb8aa3b, v62
	v_fma_f32 v101, -v93, v98, 1.0
	v_fmac_f32_e32 v98, v101, v98
	v_div_scale_f32 v101, vcc, s39, v92, s39
	v_mul_f32_e32 v102, v101, v98
	v_fma_f32 v103, -v93, v102, v101
	v_fmac_f32_e32 v102, v103, v98
	v_fma_f32 v93, -v93, v102, v101
	v_div_fmas_f32 v93, v93, v98, v102
	v_div_fixup_f32 v92, v93, v92, s39
	v_add_f32_e32 v93, v9, v96
	v_mul_f32_e32 v93, 0xbfb8aa3b, v93
	v_exp_f32_e32 v93, v93
	v_mul_f32_e32 v92, 0x3fb8aa3b, v92
	v_exp_f32_e32 v92, v92
	v_exp_f32_e32 v62, v62
	v_add_f32_e32 v93, 1.0, v93
	v_div_scale_f32 v96, s[12:13], v93, v93, s39
	v_rcp_f32_e32 v98, v96
	v_sub_f32_e32 v92, 1.0, v92
	v_add_f32_e32 v62, 1.0, v62
	v_add_u32_e32 v108, 0x3000, v109
	v_fma_f32 v101, -v96, v98, 1.0
	v_fmac_f32_e32 v98, v101, v98
	v_div_scale_f32 v101, vcc, s39, v93, s39
	v_mul_f32_e32 v102, v101, v98
	v_fma_f32 v103, -v96, v102, v101
	v_fmac_f32_e32 v102, v103, v98
	v_fma_f32 v96, -v96, v102, v101
	v_div_fmas_f32 v96, v96, v98, v102
	v_div_fixup_f32 v93, v96, v93, s39
	v_div_scale_f32 v96, s[12:13], v94, v94, 1.0
	v_rcp_f32_e32 v98, v96
	v_mul_f32_e32 v93, 0x3fb8aa3b, v93
	v_exp_f32_e32 v93, v93
	v_add_f32_e32 v63, v7, v63
	v_fma_f32 v101, -v96, v98, 1.0
	v_fmac_f32_e32 v98, v101, v98
	v_div_scale_f32 v101, vcc, 1.0, v94, 1.0
	v_mul_f32_e32 v102, v101, v98
	v_fma_f32 v103, -v96, v102, v101
	v_fmac_f32_e32 v102, v103, v98
	v_fma_f32 v96, -v96, v102, v101
	v_div_fmas_f32 v96, v96, v98, v102
	v_div_fixup_f32 v94, v96, v94, 1.0
	v_mul_f32_e32 v96, v5, v91
	v_mul_f32_e32 v98, v96, v96
	v_sub_f32_e32 v93, 1.0, v93
	v_mul_f32_e32 v63, 0xbfb8aa3b, v63
	v_mov_b32_dpp v98, v98 quad_perm:[1,0,3,2] row_mask:0xf bank_mask:0xf bound_ctrl:1
	v_fmac_f32_e32 v98, v96, v96
	v_exp_f32_e32 v63, v63
	v_add_f32_e32 v56, v11, v56
	v_add_f32_dpp v98, v98, v98 quad_perm:[2,3,0,1] row_mask:0xf bank_mask:0xf bound_ctrl:1
	v_mul_f32_e32 v56, 0xbfb8aa3b, v56
	v_add_f32_e32 v63, 1.0, v63
	v_add_f32_dpp v98, v98, v98 row_half_mirror row_mask:0xf bank_mask:0xf bound_ctrl:1
	v_exp_f32_e32 v56, v56
	v_add_f32_e32 v54, v9, v54
	v_add_f32_dpp v98, v98, v98 row_mirror row_mask:0xf bank_mask:0xf bound_ctrl:1
	v_mul_f32_e32 v54, 0xbfb8aa3b, v54
	v_readlane_b32 s13, v98, 16
	v_readlane_b32 s12, v98, 0
	v_add_f32_e32 v56, 1.0, v56
	v_mov_b32_e32 v101, s13
	v_readlane_b32 s13, v98, 48
	v_add_f32_e32 v101, s12, v101
	v_readlane_b32 s12, v98, 32
	v_mov_b32_e32 v98, s13
	v_exp_f32_e32 v54, v54
	v_add_f32_e32 v98, s12, v98
	v_add_f32_e32 v98, v101, v98
	v_max_f32_e32 v98, 0x179abe15, v98
	v_rsq_f32_e32 v98, v98
	v_add_f32_e32 v54, 1.0, v54
	v_add_f32_e32 v52, v7, v52
	v_mul_f32_e32 v52, 0xbfb8aa3b, v52
	v_mul_f32_e32 v96, v96, v98
	v_add_f32_e32 v98, -1.0, v94
	v_mul_f32_e32 v94, v94, v96
	v_cvt_pk_bf16_f32 v90, -v96, s0
	v_fma_f32 v98, v3, v98, 1.0
	ds_write_b16 v109, v90 offset:37888
	v_cvt_pk_bf16_f32 v90, v94, s0
	v_mul_f32_e32 v91, v91, v98
	ds_write_b16 v109, v90 offset:46080
	v_cvt_pk_bf16_f32 v90, v92, s0
	v_mov_b32_e32 v92, v81
	v_cvt_pk_bf16_f32 v91, v91, s0
	ds_write_b16 v109, v90 offset:54272
	v_cvt_pk_bf16_f32 v90, v93, s0
	v_fmac_f32_e32 v92, v83, v23
	v_mov_b32_e32 v83, v80
	ds_write_b16 v109, v91 offset:21504
	ds_write_b16 v109, v90 offset:62464
	v_pk_add_f32 v[90:91], v[74:75], v[80:81] neg_lo:[0,1] neg_hi:[0,1]
	v_fmac_f32_e32 v83, v82, v19
	v_sub_f32_e32 v82, v127, v126
	v_fmac_f32_e32 v83, v90, v114
	v_fma_f32 v82, v82, v1, v126
	v_sub_f32_e32 v90, v125, v126
	v_fmac_f32_e32 v82, v90, v21
	v_add_f32_e32 v90, v11, v99
	v_mul_f32_e32 v90, 0xbfb8aa3b, v90
	v_exp_f32_e32 v90, v90
	v_fmac_f32_e32 v92, v91, v115
	v_cvt_pk_bf16_f32 v98, v100, s0
	ds_write_b16 v109, v98 offset:13312
	v_add_f32_e32 v90, 1.0, v90
	v_div_scale_f32 v91, s[12:13], v90, v90, s39
	v_rcp_f32_e32 v93, v91
	v_cvt_pk_bf16_f32 v82, v82, s0
	ds_write_b16 v109, v82 offset:30208
	v_pk_add_f32 v[80:81], v[80:81], v[74:75] neg_lo:[0,1] neg_hi:[0,1]
	v_fma_f32 v94, -v91, v93, 1.0
	v_fmac_f32_e32 v93, v94, v93
	v_div_scale_f32 v94, vcc, s39, v90, s39
	v_mul_f32_e32 v96, v94, v93
	v_fma_f32 v98, -v91, v96, v94
	v_fmac_f32_e32 v96, v98, v93
	v_fma_f32 v91, -v91, v96, v94
	v_div_fmas_f32 v91, v91, v93, v96
	v_div_fixup_f32 v90, v91, v90, s39
	v_add_f32_e32 v91, v9, v97
	v_mul_f32_e32 v91, 0xbfb8aa3b, v91
	v_exp_f32_e32 v91, v91
	v_mul_f32_e32 v90, 0x3fb8aa3b, v90
	v_exp_f32_e32 v90, v90
	v_cvt_pk_bf16_f32 v92, v92, s0
	v_add_f32_e32 v91, 1.0, v91
	v_div_scale_f32 v93, s[12:13], v91, v91, s39
	v_rcp_f32_e32 v94, v93
	v_sub_f32_e32 v90, 1.0, v90
	ds_write_b16 v109, v92 offset:13824
	v_exp_f32_e32 v52, v52
	v_fma_f32 v96, -v93, v94, 1.0
	v_fmac_f32_e32 v94, v96, v94
	v_div_scale_f32 v96, vcc, s39, v91, s39
	v_mul_f32_e32 v97, v96, v94
	v_fma_f32 v98, -v93, v97, v96
	v_fmac_f32_e32 v97, v98, v94
	v_fma_f32 v93, -v93, v97, v96
	v_div_fmas_f32 v93, v93, v94, v97
	v_div_fixup_f32 v91, v93, v91, s39
	v_add_f32_e32 v93, v7, v95
	v_mul_f32_e32 v93, 0xbfb8aa3b, v93
	v_exp_f32_e32 v93, v93
	v_mul_f32_e32 v91, 0x3fb8aa3b, v91
	v_exp_f32_e32 v91, v91
	v_add_f32_e32 v52, 1.0, v52
	v_add_f32_e32 v93, 1.0, v93
	v_div_scale_f32 v94, s[12:13], v93, v93, 1.0
	v_rcp_f32_e32 v95, v94
	v_sub_f32_e32 v91, 1.0, v91
	v_add_f32_e32 v53, v7, v53
	v_mul_f32_e32 v53, 0xbfb8aa3b, v53
	v_fma_f32 v96, -v94, v95, 1.0
	v_fmac_f32_e32 v95, v96, v95
	v_div_scale_f32 v96, vcc, 1.0, v93, 1.0
	v_mul_f32_e32 v97, v96, v95
	v_fma_f32 v98, -v94, v97, v96
	v_fmac_f32_e32 v97, v98, v95
	v_fma_f32 v94, -v94, v97, v96
	v_div_fmas_f32 v94, v94, v95, v97
	v_div_fixup_f32 v93, v94, v93, 1.0
	v_mul_f32_e32 v94, v5, v83
	v_mul_f32_e32 v95, v94, v94
	v_exp_f32_e32 v53, v53
	v_add_f32_e32 v46, v11, v46
	v_mov_b32_dpp v95, v95 quad_perm:[1,0,3,2] row_mask:0xf bank_mask:0xf bound_ctrl:1
	v_fmac_f32_e32 v95, v94, v94
	v_add_f32_e32 v53, 1.0, v53
	v_mul_f32_e32 v46, 0xbfb8aa3b, v46
	v_add_f32_dpp v95, v95, v95 quad_perm:[2,3,0,1] row_mask:0xf bank_mask:0xf bound_ctrl:1
	v_exp_f32_e32 v46, v46
	v_add_f32_e32 v44, v9, v44
	v_add_f32_dpp v95, v95, v95 row_half_mirror row_mask:0xf bank_mask:0xf bound_ctrl:1
	v_mul_f32_e32 v44, 0xbfb8aa3b, v44
	v_add_f32_e32 v46, 1.0, v46
	v_add_f32_dpp v95, v95, v95 row_mirror row_mask:0xf bank_mask:0xf bound_ctrl:1
	v_exp_f32_e32 v44, v44
	v_readlane_b32 s13, v95, 16
	v_readlane_b32 s12, v95, 0
	v_add_f32_e32 v42, v7, v42
	v_mov_b32_e32 v96, s13
	v_readlane_b32 s13, v95, 48
	v_add_f32_e32 v96, s12, v96
	v_readlane_b32 s12, v95, 32
	v_mov_b32_e32 v95, s13
	v_add_f32_e32 v44, 1.0, v44
	v_add_f32_e32 v95, s12, v95
	v_add_f32_e32 v95, v96, v95
	v_max_f32_e32 v95, 0x179abe15, v95
	v_rsq_f32_e32 v95, v95
	v_mul_f32_e32 v42, 0xbfb8aa3b, v42
	v_exp_f32_e32 v42, v42
	v_add_f32_e32 v43, v7, v43
	v_mul_f32_e32 v94, v94, v95
	v_add_f32_e32 v95, -1.0, v93
	v_mul_f32_e32 v93, v93, v94
	v_cvt_pk_bf16_f32 v82, -v94, s0
	v_fma_f32 v95, v3, v95, 1.0
	ds_write_b16 v109, v82 offset:38400
	v_cvt_pk_bf16_f32 v82, v93, s0
	v_mul_f32_e32 v83, v83, v95
	ds_write_b16 v109, v82 offset:46592
	v_cvt_pk_bf16_f32 v82, v90, s0
	v_mov_b32_e32 v90, v75
	v_cvt_pk_bf16_f32 v83, v83, s0
	ds_write_b16 v109, v82 offset:54784
	v_cvt_pk_bf16_f32 v82, v91, s0
	v_fmac_f32_e32 v90, v81, v23
	v_mov_b32_e32 v81, v74
	ds_write_b16 v109, v83 offset:22016
	ds_write_b16 v109, v82 offset:62976
	v_pk_add_f32 v[82:83], v[70:71], v[74:75] neg_lo:[0,1] neg_hi:[0,1]
	v_fmac_f32_e32 v81, v80, v19
	v_sub_f32_e32 v80, v126, v125
	v_fmac_f32_e32 v81, v82, v114
	v_fma_f32 v80, v80, v1, v125
	v_sub_f32_e32 v82, v124, v125
	v_fmac_f32_e32 v80, v82, v21
	v_add_f32_e32 v82, v11, v88
	v_mul_f32_e32 v82, 0xbfb8aa3b, v82
	v_exp_f32_e32 v82, v82
	v_fmac_f32_e32 v90, v83, v115
	v_cvt_pk_bf16_f32 v80, v80, s0
	ds_write_b16 v109, v80 offset:30720
	v_add_f32_e32 v82, 1.0, v82
	v_div_scale_f32 v83, s[12:13], v82, v82, s39
	v_rcp_f32_e32 v88, v83
	v_pk_add_f32 v[74:75], v[74:75], v[70:71] neg_lo:[0,1] neg_hi:[0,1]
	v_add_f32_e32 v42, 1.0, v42
	v_mul_f32_e32 v43, 0xbfb8aa3b, v43
	v_fma_f32 v91, -v83, v88, 1.0
	v_fmac_f32_e32 v88, v91, v88
	v_div_scale_f32 v91, vcc, s39, v82, s39
	v_mul_f32_e32 v92, v91, v88
	v_fma_f32 v93, -v83, v92, v91
	v_fmac_f32_e32 v92, v93, v88
	v_fma_f32 v83, -v83, v92, v91
	v_div_fmas_f32 v83, v83, v88, v92
	v_div_fixup_f32 v82, v83, v82, s39
	v_add_f32_e32 v83, v9, v86
	v_mul_f32_e32 v83, 0xbfb8aa3b, v83
	v_exp_f32_e32 v83, v83
	v_mul_f32_e32 v82, 0x3fb8aa3b, v82
	v_exp_f32_e32 v82, v82
	v_exp_f32_e32 v43, v43
	v_add_f32_e32 v83, 1.0, v83
	v_div_scale_f32 v86, s[12:13], v83, v83, s39
	v_rcp_f32_e32 v88, v86
	v_sub_f32_e32 v82, 1.0, v82
	v_add_f32_e32 v43, 1.0, v43
	v_add_f32_e32 v36, v11, v36
	v_fma_f32 v91, -v86, v88, 1.0
	v_fmac_f32_e32 v88, v91, v88
	v_div_scale_f32 v91, vcc, s39, v83, s39
	v_mul_f32_e32 v92, v91, v88
	v_fma_f32 v93, -v86, v92, v91
	v_fmac_f32_e32 v92, v93, v88
	v_fma_f32 v86, -v86, v92, v91
	v_div_fmas_f32 v86, v86, v88, v92
	v_div_fixup_f32 v83, v86, v83, s39
	v_div_scale_f32 v86, s[12:13], v84, v84, 1.0
	v_rcp_f32_e32 v88, v86
	v_mul_f32_e32 v83, 0x3fb8aa3b, v83
	v_exp_f32_e32 v83, v83
	v_mul_f32_e32 v36, 0xbfb8aa3b, v36
	v_fma_f32 v91, -v86, v88, 1.0
	v_fmac_f32_e32 v88, v91, v88
	v_div_scale_f32 v91, vcc, 1.0, v84, 1.0
	v_mul_f32_e32 v92, v91, v88
	v_fma_f32 v93, -v86, v92, v91
	v_fmac_f32_e32 v92, v93, v88
	v_fma_f32 v86, -v86, v92, v91
	v_div_fmas_f32 v86, v86, v88, v92
	v_div_fixup_f32 v84, v86, v84, 1.0
	v_mul_f32_e32 v86, v5, v81
	v_mul_f32_e32 v88, v86, v86
	v_sub_f32_e32 v83, 1.0, v83
	v_exp_f32_e32 v36, v36
	v_mov_b32_dpp v88, v88 quad_perm:[1,0,3,2] row_mask:0xf bank_mask:0xf bound_ctrl:1
	v_fmac_f32_e32 v88, v86, v86
	v_add_f32_e32 v34, v9, v34
	v_add_f32_e32 v36, 1.0, v36
	v_add_f32_dpp v88, v88, v88 quad_perm:[2,3,0,1] row_mask:0xf bank_mask:0xf bound_ctrl:1
	v_mul_f32_e32 v34, 0xbfb8aa3b, v34
	v_exp_f32_e32 v34, v34
	v_add_f32_dpp v88, v88, v88 row_half_mirror row_mask:0xf bank_mask:0xf bound_ctrl:1
	v_add_f32_e32 v30, v7, v30
	v_mul_f32_e32 v30, 0xbfb8aa3b, v30
	v_add_f32_dpp v88, v88, v88 row_mirror row_mask:0xf bank_mask:0xf bound_ctrl:1
	v_add_f32_e32 v34, 1.0, v34
	v_readlane_b32 s13, v88, 16
	v_readlane_b32 s12, v88, 0
	v_exp_f32_e32 v30, v30
	v_mov_b32_e32 v91, s13
	v_readlane_b32 s13, v88, 48
	v_add_f32_e32 v91, s12, v91
	v_readlane_b32 s12, v88, 32
	v_mov_b32_e32 v88, s13
	v_add_f32_e32 v30, 1.0, v30
	v_add_f32_e32 v88, s12, v88
	v_add_f32_e32 v88, v91, v88
	v_max_f32_e32 v88, 0x179abe15, v88
	v_rsq_f32_e32 v88, v88
	v_sub_f32_e32 v17, v17, v13
	v_pk_add_f32 v[28:29], v[28:29], v[24:25] neg_lo:[0,1] neg_hi:[0,1]
	v_cvt_pk_bf16_f32 v111, v112, s0
	v_mul_f32_e32 v86, v86, v88
	v_add_f32_e32 v88, -1.0, v84
	v_mul_f32_e32 v84, v84, v86
	v_cvt_pk_bf16_f32 v80, -v86, s0
	v_fma_f32 v88, v3, v88, 1.0
	ds_write_b16 v109, v80 offset:38912
	v_cvt_pk_bf16_f32 v80, v84, s0
	v_mul_f32_e32 v81, v81, v88
	ds_write_b16 v109, v80 offset:47104
	v_cvt_pk_bf16_f32 v80, v82, s0
	v_mov_b32_e32 v82, v71
	v_cvt_pk_bf16_f32 v81, v81, s0
	ds_write_b16 v109, v80 offset:55296
	v_cvt_pk_bf16_f32 v80, v83, s0
	v_fmac_f32_e32 v82, v75, v23
	v_mov_b32_e32 v75, v70
	ds_write_b16 v109, v81 offset:22528
	ds_write_b16 v109, v80 offset:63488
	v_pk_add_f32 v[80:81], v[66:67], v[70:71] neg_lo:[0,1] neg_hi:[0,1]
	v_fmac_f32_e32 v75, v74, v19
	v_sub_f32_e32 v74, v125, v124
	v_fmac_f32_e32 v75, v80, v114
	v_fma_f32 v74, v74, v1, v124
	v_sub_f32_e32 v80, v123, v124
	v_fmac_f32_e32 v74, v80, v21
	v_add_f32_e32 v80, v11, v89
	v_mul_f32_e32 v80, 0xbfb8aa3b, v80
	v_exp_f32_e32 v80, v80
	v_fmac_f32_e32 v82, v81, v115
	v_cvt_pk_bf16_f32 v88, v90, s0
	ds_write_b16 v109, v88 offset:14336
	v_add_f32_e32 v80, 1.0, v80
	v_div_scale_f32 v81, s[12:13], v80, v80, s39
	v_rcp_f32_e32 v83, v81
	v_cvt_pk_bf16_f32 v74, v74, s0
	ds_write_b16 v109, v74 offset:31232
	v_pk_add_f32 v[70:71], v[70:71], v[66:67] neg_lo:[0,1] neg_hi:[0,1]
	v_fma_f32 v84, -v81, v83, 1.0
	v_fmac_f32_e32 v83, v84, v83
	v_div_scale_f32 v84, vcc, s39, v80, s39
	v_mul_f32_e32 v86, v84, v83
	v_fma_f32 v88, -v81, v86, v84
	v_fmac_f32_e32 v86, v88, v83
	v_fma_f32 v81, -v81, v86, v84
	v_div_fmas_f32 v81, v81, v83, v86
	v_div_fixup_f32 v80, v81, v80, s39
	v_add_f32_e32 v81, v9, v87
	v_mul_f32_e32 v81, 0xbfb8aa3b, v81
	v_exp_f32_e32 v81, v81
	v_mul_f32_e32 v80, 0x3fb8aa3b, v80
	v_exp_f32_e32 v80, v80
	v_cvt_pk_bf16_f32 v82, v82, s0
	v_add_f32_e32 v81, 1.0, v81
	v_div_scale_f32 v83, s[12:13], v81, v81, s39
	v_rcp_f32_e32 v84, v83
	v_sub_f32_e32 v80, 1.0, v80
	ds_write_b16 v109, v82 offset:14848
	ds_write_b16 v109, v111 offset:12288
	v_fma_f32 v86, -v83, v84, 1.0
	v_fmac_f32_e32 v84, v86, v84
	v_div_scale_f32 v86, vcc, s39, v81, s39
	v_mul_f32_e32 v87, v86, v84
	v_fma_f32 v88, -v83, v87, v86
	v_fmac_f32_e32 v87, v88, v84
	v_fma_f32 v83, -v83, v87, v86
	v_div_fmas_f32 v83, v83, v84, v87
	v_div_fixup_f32 v81, v83, v81, s39
	v_add_f32_e32 v83, v7, v85
	v_mul_f32_e32 v83, 0xbfb8aa3b, v83
	v_exp_f32_e32 v83, v83
	v_mul_f32_e32 v81, 0x3fb8aa3b, v81
	v_exp_f32_e32 v81, v81
	v_add_f32_e32 v7, v7, v31
	v_add_f32_e32 v83, 1.0, v83
	v_div_scale_f32 v84, s[12:13], v83, v83, 1.0
	v_rcp_f32_e32 v85, v84
	v_sub_f32_e32 v81, 1.0, v81
	v_mul_f32_e32 v7, 0xbfb8aa3b, v7
	v_exp_f32_e32 v7, v7
	v_fma_f32 v86, -v84, v85, 1.0
	v_fmac_f32_e32 v85, v86, v85
	v_div_scale_f32 v86, vcc, 1.0, v83, 1.0
	v_mul_f32_e32 v87, v86, v85
	v_fma_f32 v88, -v84, v87, v86
	v_fmac_f32_e32 v87, v88, v85
	v_fma_f32 v84, -v84, v87, v86
	v_div_fmas_f32 v84, v84, v85, v87
	v_div_fixup_f32 v83, v84, v83, 1.0
	v_mul_f32_e32 v84, v5, v75
	v_mul_f32_e32 v85, v84, v84
	v_add_f32_e32 v7, 1.0, v7
	s_add_i32 s19, s19, s38
	v_mov_b32_dpp v85, v85 quad_perm:[1,0,3,2] row_mask:0xf bank_mask:0xf bound_ctrl:1
	v_fmac_f32_e32 v85, v84, v84
	s_cmpk_gt_i32 s19, 0xbff
	s_nop 0
	v_add_f32_dpp v85, v85, v85 quad_perm:[2,3,0,1] row_mask:0xf bank_mask:0xf bound_ctrl:1
	s_nop 1
	v_add_f32_dpp v85, v85, v85 row_half_mirror row_mask:0xf bank_mask:0xf bound_ctrl:1
	s_nop 1
	v_add_f32_dpp v85, v85, v85 row_mirror row_mask:0xf bank_mask:0xf bound_ctrl:1
	s_nop 0
	v_readlane_b32 s13, v85, 16
	v_readlane_b32 s12, v85, 0
	s_nop 0
	v_mov_b32_e32 v86, s13
	v_readlane_b32 s13, v85, 48
	v_add_f32_e32 v86, s12, v86
	v_readlane_b32 s12, v85, 32
	v_mov_b32_e32 v85, s13
	s_nop 0
	v_add_f32_e32 v85, s12, v85
	v_add_f32_e32 v85, v86, v85
	v_max_f32_e32 v85, 0x179abe15, v85
	v_rsq_f32_e32 v85, v85
	s_nop 0
	v_mul_f32_e32 v84, v84, v85
	v_add_f32_e32 v85, -1.0, v83
	v_mul_f32_e32 v83, v83, v84
	v_cvt_pk_bf16_f32 v74, -v84, s0
	v_fma_f32 v85, v3, v85, 1.0
	ds_write_b16 v109, v74 offset:39424
	v_cvt_pk_bf16_f32 v74, v83, s0
	v_mul_f32_e32 v75, v75, v85
	ds_write_b16 v109, v74 offset:47616
	v_cvt_pk_bf16_f32 v74, v80, s0
	v_mov_b32_e32 v80, v67
	v_cvt_pk_bf16_f32 v75, v75, s0
	ds_write_b16 v109, v74 offset:55808
	v_cvt_pk_bf16_f32 v74, v81, s0
	v_fmac_f32_e32 v80, v71, v23
	v_mov_b32_e32 v71, v66
	ds_write_b16 v109, v75 offset:23040
	ds_write_b16 v109, v74 offset:64000
	v_pk_add_f32 v[74:75], v[60:61], v[66:67] neg_lo:[0,1] neg_hi:[0,1]
	v_fmac_f32_e32 v71, v70, v19
	v_sub_f32_e32 v70, v124, v123
	v_fmac_f32_e32 v71, v74, v114
	v_fma_f32 v70, v70, v1, v123
	v_sub_f32_e32 v74, v122, v123
	v_fmac_f32_e32 v70, v74, v21
	v_add_f32_e32 v74, v11, v78
	v_mul_f32_e32 v74, 0xbfb8aa3b, v74
	v_exp_f32_e32 v74, v74
	v_fmac_f32_e32 v80, v75, v115
	v_cvt_pk_bf16_f32 v70, v70, s0
	ds_write_b16 v109, v70 offset:31744
	v_add_f32_e32 v74, 1.0, v74
	v_div_scale_f32 v75, s[12:13], v74, v74, s39
	v_rcp_f32_e32 v78, v75
	v_pk_add_f32 v[66:67], v[66:67], v[60:61] neg_lo:[0,1] neg_hi:[0,1]
	v_fma_f32 v81, -v75, v78, 1.0
	v_fmac_f32_e32 v78, v81, v78
	v_div_scale_f32 v81, vcc, s39, v74, s39
	v_mul_f32_e32 v82, v81, v78
	v_fma_f32 v83, -v75, v82, v81
	v_fmac_f32_e32 v82, v83, v78
	v_fma_f32 v75, -v75, v82, v81
	v_div_fmas_f32 v75, v75, v78, v82
	v_div_fixup_f32 v74, v75, v74, s39
	v_add_f32_e32 v75, v9, v76
	v_mul_f32_e32 v75, 0xbfb8aa3b, v75
	v_exp_f32_e32 v75, v75
	v_mul_f32_e32 v74, 0x3fb8aa3b, v74
	v_exp_f32_e32 v74, v74
	v_add_f32_e32 v75, 1.0, v75
	v_div_scale_f32 v76, s[12:13], v75, v75, s39
	v_rcp_f32_e32 v78, v76
	v_sub_f32_e32 v74, 1.0, v74
	v_fma_f32 v81, -v76, v78, 1.0
	v_fmac_f32_e32 v78, v81, v78
	v_div_scale_f32 v81, vcc, s39, v75, s39
	v_mul_f32_e32 v82, v81, v78
	v_fma_f32 v83, -v76, v82, v81
	v_fmac_f32_e32 v82, v83, v78
	v_fma_f32 v76, -v76, v82, v81
	v_div_fmas_f32 v76, v76, v78, v82
	v_div_fixup_f32 v75, v76, v75, s39
	v_div_scale_f32 v76, s[12:13], v72, v72, 1.0
	v_rcp_f32_e32 v78, v76
	v_mul_f32_e32 v75, 0x3fb8aa3b, v75
	v_exp_f32_e32 v75, v75
	v_fma_f32 v81, -v76, v78, 1.0
	v_fmac_f32_e32 v78, v81, v78
	v_div_scale_f32 v81, vcc, 1.0, v72, 1.0
	v_mul_f32_e32 v82, v81, v78
	v_fma_f32 v83, -v76, v82, v81
	v_fmac_f32_e32 v82, v83, v78
	v_fma_f32 v76, -v76, v82, v81
	v_div_fmas_f32 v76, v76, v78, v82
	v_div_fixup_f32 v72, v76, v72, 1.0
	v_mul_f32_e32 v76, v5, v71
	v_mul_f32_e32 v78, v76, v76
	v_sub_f32_e32 v75, 1.0, v75
	s_nop 0
	v_mov_b32_dpp v78, v78 quad_perm:[1,0,3,2] row_mask:0xf bank_mask:0xf bound_ctrl:1
	v_fmac_f32_e32 v78, v76, v76
	s_nop 1
	v_add_f32_dpp v78, v78, v78 quad_perm:[2,3,0,1] row_mask:0xf bank_mask:0xf bound_ctrl:1
	s_nop 1
	v_add_f32_dpp v78, v78, v78 row_half_mirror row_mask:0xf bank_mask:0xf bound_ctrl:1
	s_nop 1
	v_add_f32_dpp v78, v78, v78 row_mirror row_mask:0xf bank_mask:0xf bound_ctrl:1
	s_nop 0
	v_readlane_b32 s13, v78, 16
	v_readlane_b32 s12, v78, 0
	s_nop 0
	v_mov_b32_e32 v81, s13
	v_readlane_b32 s13, v78, 48
	v_add_f32_e32 v81, s12, v81
	v_readlane_b32 s12, v78, 32
	v_mov_b32_e32 v78, s13
	s_nop 0
	v_add_f32_e32 v78, s12, v78
	v_add_f32_e32 v78, v81, v78
	v_max_f32_e32 v78, 0x179abe15, v78
	v_rsq_f32_e32 v78, v78
	s_nop 0
	v_mul_f32_e32 v76, v76, v78
	v_add_f32_e32 v78, -1.0, v72
	v_mul_f32_e32 v72, v72, v76
	v_cvt_pk_bf16_f32 v70, -v76, s0
	v_fma_f32 v78, v3, v78, 1.0
	ds_write_b16 v109, v70 offset:39936
	v_cvt_pk_bf16_f32 v70, v72, s0
	v_mul_f32_e32 v71, v71, v78
	ds_write_b16 v109, v70 offset:48128
	v_cvt_pk_bf16_f32 v70, v74, s0
	v_mov_b32_e32 v72, v61
	v_cvt_pk_bf16_f32 v71, v71, s0
	ds_write_b16 v109, v70 offset:56320
	v_cvt_pk_bf16_f32 v70, v75, s0
	v_fmac_f32_e32 v72, v67, v23
	v_mov_b32_e32 v67, v60
	ds_write_b16 v109, v71 offset:23552
	ds_write_b16 v109, v70 offset:64512
	v_pk_add_f32 v[70:71], v[58:59], v[60:61] neg_lo:[0,1] neg_hi:[0,1]
	v_fmac_f32_e32 v67, v66, v19
	v_sub_f32_e32 v66, v123, v122
	v_fmac_f32_e32 v67, v70, v114
	v_fma_f32 v66, v66, v1, v122
	v_sub_f32_e32 v70, v121, v122
	v_fmac_f32_e32 v66, v70, v21
	v_add_f32_e32 v70, v11, v79
	v_mul_f32_e32 v70, 0xbfb8aa3b, v70
	v_exp_f32_e32 v70, v70
	v_fmac_f32_e32 v72, v71, v115
	v_cvt_pk_bf16_f32 v78, v80, s0
	ds_write_b16 v109, v78 offset:15360
	v_add_f32_e32 v70, 1.0, v70
	v_div_scale_f32 v71, s[12:13], v70, v70, s39
	v_rcp_f32_e32 v74, v71
	v_cvt_pk_bf16_f32 v66, v66, s0
	ds_write_b16 v109, v66 offset:32256
	v_pk_add_f32 v[60:61], v[60:61], v[58:59] neg_lo:[0,1] neg_hi:[0,1]
	v_fma_f32 v75, -v71, v74, 1.0
	v_fmac_f32_e32 v74, v75, v74
	v_div_scale_f32 v75, vcc, s39, v70, s39
	v_mul_f32_e32 v76, v75, v74
	v_fma_f32 v78, -v71, v76, v75
	v_fmac_f32_e32 v76, v78, v74
	v_fma_f32 v71, -v71, v76, v75
	v_div_fmas_f32 v71, v71, v74, v76
	v_div_fixup_f32 v70, v71, v70, s39
	v_add_f32_e32 v71, v9, v77
	v_mul_f32_e32 v71, 0xbfb8aa3b, v71
	v_exp_f32_e32 v71, v71
	v_mul_f32_e32 v70, 0x3fb8aa3b, v70
	v_exp_f32_e32 v70, v70
	v_cvt_pk_bf16_f32 v72, v72, s0
	v_add_f32_e32 v71, 1.0, v71
	v_div_scale_f32 v74, s[12:13], v71, v71, s39
	v_rcp_f32_e32 v75, v74
	v_sub_f32_e32 v70, 1.0, v70
	ds_write_b16 v109, v72 offset:15872
	v_fma_f32 v76, -v74, v75, 1.0
	v_fmac_f32_e32 v75, v76, v75
	v_div_scale_f32 v76, vcc, s39, v71, s39
	v_mul_f32_e32 v77, v76, v75
	v_fma_f32 v78, -v74, v77, v76
	v_fmac_f32_e32 v77, v78, v75
	v_fma_f32 v74, -v74, v77, v76
	v_div_fmas_f32 v74, v74, v75, v77
	v_div_fixup_f32 v71, v74, v71, s39
	v_div_scale_f32 v74, s[12:13], v73, v73, 1.0
	v_rcp_f32_e32 v75, v74
	v_mul_f32_e32 v71, 0x3fb8aa3b, v71
	v_exp_f32_e32 v71, v71
	v_fma_f32 v76, -v74, v75, 1.0
	v_fmac_f32_e32 v75, v76, v75
	v_div_scale_f32 v76, vcc, 1.0, v73, 1.0
	v_mul_f32_e32 v77, v76, v75
	v_fma_f32 v78, -v74, v77, v76
	v_fmac_f32_e32 v77, v78, v75
	v_fma_f32 v74, -v74, v77, v76
	v_div_fmas_f32 v74, v74, v75, v77
	v_div_fixup_f32 v73, v74, v73, 1.0
	v_mul_f32_e32 v74, v5, v67
	v_mul_f32_e32 v75, v74, v74
	v_sub_f32_e32 v71, 1.0, v71
	s_nop 0
	v_mov_b32_dpp v75, v75 quad_perm:[1,0,3,2] row_mask:0xf bank_mask:0xf bound_ctrl:1
	v_fmac_f32_e32 v75, v74, v74
	s_nop 1
	v_add_f32_dpp v75, v75, v75 quad_perm:[2,3,0,1] row_mask:0xf bank_mask:0xf bound_ctrl:1
	s_nop 1
	v_add_f32_dpp v75, v75, v75 row_half_mirror row_mask:0xf bank_mask:0xf bound_ctrl:1
	s_nop 1
	v_add_f32_dpp v75, v75, v75 row_mirror row_mask:0xf bank_mask:0xf bound_ctrl:1
	s_nop 0
	v_readlane_b32 s13, v75, 16
	v_readlane_b32 s12, v75, 0
	s_nop 0
	v_mov_b32_e32 v76, s13
	v_readlane_b32 s13, v75, 48
	v_add_f32_e32 v76, s12, v76
	v_readlane_b32 s12, v75, 32
	v_mov_b32_e32 v75, s13
	s_nop 0
	v_add_f32_e32 v75, s12, v75
	v_add_f32_e32 v75, v76, v75
	v_max_f32_e32 v75, 0x179abe15, v75
	v_rsq_f32_e32 v75, v75
	s_nop 0
	v_mul_f32_e32 v74, v74, v75
	v_add_f32_e32 v75, -1.0, v73
	v_mul_f32_e32 v73, v73, v74
	v_cvt_pk_bf16_f32 v66, -v74, s0
	v_fma_f32 v75, v3, v75, 1.0
	ds_write_b16 v109, v66 offset:40448
	v_cvt_pk_bf16_f32 v66, v73, s0
	v_mul_f32_e32 v67, v67, v75
	ds_write_b16 v109, v66 offset:48640
	v_cvt_pk_bf16_f32 v66, v70, s0
	v_mov_b32_e32 v70, v59
	v_cvt_pk_bf16_f32 v67, v67, s0
	ds_write_b16 v109, v66 offset:56832
	v_cvt_pk_bf16_f32 v66, v71, s0
	v_fmac_f32_e32 v70, v61, v23
	v_mov_b32_e32 v61, v58
	ds_write_b16 v109, v67 offset:24064
	ds_write_b16 v109, v66 offset:65024
	v_pk_add_f32 v[66:67], v[50:51], v[58:59] neg_lo:[0,1] neg_hi:[0,1]
	v_fmac_f32_e32 v61, v60, v19
	v_sub_f32_e32 v60, v122, v121
	v_fmac_f32_e32 v61, v66, v114
	v_fma_f32 v60, v60, v1, v121
	v_sub_f32_e32 v66, v120, v121
	v_fmac_f32_e32 v60, v66, v21
	v_add_f32_e32 v66, v11, v68
	v_mul_f32_e32 v66, 0xbfb8aa3b, v66
	v_exp_f32_e32 v66, v66
	v_fmac_f32_e32 v70, v67, v115
	v_cvt_pk_bf16_f32 v60, v60, s0
	ds_write_b16 v109, v60 offset:32768
	v_add_f32_e32 v66, 1.0, v66
	v_div_scale_f32 v67, s[12:13], v66, v66, s39
	v_rcp_f32_e32 v68, v67
	v_pk_add_f32 v[58:59], v[58:59], v[50:51] neg_lo:[0,1] neg_hi:[0,1]
	v_fma_f32 v71, -v67, v68, 1.0
	v_fmac_f32_e32 v68, v71, v68
	v_div_scale_f32 v71, vcc, s39, v66, s39
	v_mul_f32_e32 v72, v71, v68
	v_fma_f32 v73, -v67, v72, v71
	v_fmac_f32_e32 v72, v73, v68
	v_fma_f32 v67, -v67, v72, v71
	v_div_fmas_f32 v67, v67, v68, v72
	v_div_fixup_f32 v66, v67, v66, s39
	v_div_scale_f32 v67, s[12:13], v64, v64, s39
	v_rcp_f32_e32 v68, v67
	v_mul_f32_e32 v66, 0x3fb8aa3b, v66
	v_exp_f32_e32 v66, v66
	v_fma_f32 v71, -v67, v68, 1.0
	v_fmac_f32_e32 v68, v71, v68
	v_div_scale_f32 v71, vcc, s39, v64, s39
	v_mul_f32_e32 v72, v71, v68
	v_fma_f32 v73, -v67, v72, v71
	v_fmac_f32_e32 v72, v73, v68
	v_fma_f32 v67, -v67, v72, v71
	v_div_fmas_f32 v67, v67, v68, v72
	v_div_fixup_f32 v64, v67, v64, s39
	v_div_scale_f32 v67, s[12:13], v62, v62, 1.0
	v_rcp_f32_e32 v68, v67
	v_mul_f32_e32 v64, 0x3fb8aa3b, v64
	v_exp_f32_e32 v64, v64
	v_sub_f32_e32 v66, 1.0, v66
	v_fma_f32 v71, -v67, v68, 1.0
	v_fmac_f32_e32 v68, v71, v68
	v_div_scale_f32 v71, vcc, 1.0, v62, 1.0
	v_mul_f32_e32 v72, v71, v68
	v_fma_f32 v73, -v67, v72, v71
	v_fmac_f32_e32 v72, v73, v68
	v_fma_f32 v67, -v67, v72, v71
	v_div_fmas_f32 v67, v67, v68, v72
	v_div_fixup_f32 v62, v67, v62, 1.0
	v_mul_f32_e32 v67, v5, v61
	v_mul_f32_e32 v68, v67, v67
	v_sub_f32_e32 v64, 1.0, v64
	s_nop 0
	v_mov_b32_dpp v68, v68 quad_perm:[1,0,3,2] row_mask:0xf bank_mask:0xf bound_ctrl:1
	v_fmac_f32_e32 v68, v67, v67
	s_nop 1
	v_add_f32_dpp v68, v68, v68 quad_perm:[2,3,0,1] row_mask:0xf bank_mask:0xf bound_ctrl:1
	s_nop 1
	v_add_f32_dpp v68, v68, v68 row_half_mirror row_mask:0xf bank_mask:0xf bound_ctrl:1
	s_nop 1
	v_add_f32_dpp v68, v68, v68 row_mirror row_mask:0xf bank_mask:0xf bound_ctrl:1
	s_nop 0
	v_readlane_b32 s13, v68, 16
	v_readlane_b32 s12, v68, 0
	s_nop 0
	v_mov_b32_e32 v71, s13
	v_readlane_b32 s13, v68, 48
	v_add_f32_e32 v71, s12, v71
	v_readlane_b32 s12, v68, 32
	v_mov_b32_e32 v68, s13
	s_nop 0
	v_add_f32_e32 v68, s12, v68
	v_add_f32_e32 v68, v71, v68
	v_max_f32_e32 v68, 0x179abe15, v68
	v_rsq_f32_e32 v68, v68
	s_nop 0
	v_mul_f32_e32 v67, v67, v68
	v_add_f32_e32 v68, -1.0, v62
	v_mul_f32_e32 v62, v62, v67
	v_cvt_pk_bf16_f32 v60, -v67, s0
	v_fma_f32 v68, v3, v68, 1.0
	ds_write_b16 v109, v60 offset:40960
	v_cvt_pk_bf16_f32 v60, v62, s0
	v_mul_f32_e32 v61, v61, v68
	ds_write_b16 v109, v60 offset:49152
	v_cvt_pk_bf16_f32 v60, v66, s0
	v_mov_b32_e32 v62, v51
	v_cvt_pk_bf16_f32 v61, v61, s0
	ds_write_b16 v109, v60 offset:57344
	v_cvt_pk_bf16_f32 v60, v64, s0
	v_fmac_f32_e32 v62, v59, v23
	v_mov_b32_e32 v59, v50
	ds_write_b16 v109, v61 offset:24576
	ds_write_b16 v108, v60 offset:53248
	v_pk_add_f32 v[60:61], v[48:49], v[50:51] neg_lo:[0,1] neg_hi:[0,1]
	v_fmac_f32_e32 v59, v58, v19
	v_sub_f32_e32 v58, v121, v120
	v_fmac_f32_e32 v59, v60, v114
	v_fma_f32 v58, v58, v1, v120
	v_sub_f32_e32 v60, v119, v120
	v_fmac_f32_e32 v58, v60, v21
	v_add_f32_e32 v60, v11, v69
	v_mul_f32_e32 v60, 0xbfb8aa3b, v60
	v_exp_f32_e32 v60, v60
	v_fmac_f32_e32 v62, v61, v115
	v_cvt_pk_bf16_f32 v68, v70, s0
	ds_write_b16 v109, v68 offset:16384
	v_add_f32_e32 v60, 1.0, v60
	v_div_scale_f32 v61, s[12:13], v60, v60, s39
	v_rcp_f32_e32 v64, v61
	v_cvt_pk_bf16_f32 v58, v58, s0
	ds_write_b16 v109, v58 offset:33280
	v_pk_add_f32 v[50:51], v[50:51], v[48:49] neg_lo:[0,1] neg_hi:[0,1]
	v_fma_f32 v66, -v61, v64, 1.0
	v_fmac_f32_e32 v64, v66, v64
	v_div_scale_f32 v66, vcc, s39, v60, s39
	v_mul_f32_e32 v67, v66, v64
	v_fma_f32 v68, -v61, v67, v66
	v_fmac_f32_e32 v67, v68, v64
	v_fma_f32 v61, -v61, v67, v66
	v_div_fmas_f32 v61, v61, v64, v67
	v_div_fixup_f32 v60, v61, v60, s39
	v_add_f32_e32 v61, v9, v65
	v_mul_f32_e32 v61, 0xbfb8aa3b, v61
	v_exp_f32_e32 v61, v61
	v_mul_f32_e32 v60, 0x3fb8aa3b, v60
	v_exp_f32_e32 v60, v60
	v_cvt_pk_bf16_f32 v62, v62, s0
	v_add_f32_e32 v61, 1.0, v61
	v_div_scale_f32 v64, s[12:13], v61, v61, s39
	v_rcp_f32_e32 v65, v64
	v_sub_f32_e32 v60, 1.0, v60
	ds_write_b16 v109, v62 offset:16896
	v_fma_f32 v66, -v64, v65, 1.0
	v_fmac_f32_e32 v65, v66, v65
	v_div_scale_f32 v66, vcc, s39, v61, s39
	v_mul_f32_e32 v67, v66, v65
	v_fma_f32 v68, -v64, v67, v66
	v_fmac_f32_e32 v67, v68, v65
	v_fma_f32 v64, -v64, v67, v66
	v_div_fmas_f32 v64, v64, v65, v67
	v_div_fixup_f32 v61, v64, v61, s39
	v_div_scale_f32 v64, s[12:13], v63, v63, 1.0
	v_rcp_f32_e32 v65, v64
	v_mul_f32_e32 v61, 0x3fb8aa3b, v61
	v_exp_f32_e32 v61, v61
	v_fma_f32 v66, -v64, v65, 1.0
	v_fmac_f32_e32 v65, v66, v65
	v_div_scale_f32 v66, vcc, 1.0, v63, 1.0
	v_mul_f32_e32 v67, v66, v65
	v_fma_f32 v68, -v64, v67, v66
	v_fmac_f32_e32 v67, v68, v65
	v_fma_f32 v64, -v64, v67, v66
	v_div_fmas_f32 v64, v64, v65, v67
	v_div_fixup_f32 v63, v64, v63, 1.0
	v_mul_f32_e32 v64, v5, v59
	v_mul_f32_e32 v65, v64, v64
	v_sub_f32_e32 v61, 1.0, v61
	s_nop 0
	v_mov_b32_dpp v65, v65 quad_perm:[1,0,3,2] row_mask:0xf bank_mask:0xf bound_ctrl:1
	v_fmac_f32_e32 v65, v64, v64
	s_nop 1
	v_add_f32_dpp v65, v65, v65 quad_perm:[2,3,0,1] row_mask:0xf bank_mask:0xf bound_ctrl:1
	s_nop 1
	v_add_f32_dpp v65, v65, v65 row_half_mirror row_mask:0xf bank_mask:0xf bound_ctrl:1
	s_nop 1
	v_add_f32_dpp v65, v65, v65 row_mirror row_mask:0xf bank_mask:0xf bound_ctrl:1
	s_nop 0
	v_readlane_b32 s13, v65, 16
	v_readlane_b32 s12, v65, 0
	s_nop 0
	v_mov_b32_e32 v66, s13
	v_readlane_b32 s13, v65, 48
	v_add_f32_e32 v66, s12, v66
	v_readlane_b32 s12, v65, 32
	v_mov_b32_e32 v65, s13
	s_nop 0
	v_add_f32_e32 v65, s12, v65
	v_add_f32_e32 v65, v66, v65
	v_max_f32_e32 v65, 0x179abe15, v65
	v_rsq_f32_e32 v65, v65
	s_nop 0
	v_mul_f32_e32 v64, v64, v65
	v_add_f32_e32 v65, -1.0, v63
	v_mul_f32_e32 v63, v63, v64
	v_cvt_pk_bf16_f32 v58, -v64, s0
	v_fma_f32 v65, v3, v65, 1.0
	ds_write_b16 v109, v58 offset:41472
	v_cvt_pk_bf16_f32 v58, v63, s0
	v_mul_f32_e32 v59, v59, v65
	ds_write_b16 v109, v58 offset:49664
	v_cvt_pk_bf16_f32 v58, v60, s0
	v_mov_b32_e32 v60, v49
	v_cvt_pk_bf16_f32 v59, v59, s0
	ds_write_b16 v109, v58 offset:57856
	v_cvt_pk_bf16_f32 v58, v61, s0
	v_fmac_f32_e32 v60, v51, v23
	v_mov_b32_e32 v51, v48
	ds_write_b16 v109, v59 offset:25088
	ds_write_b16 v108, v58 offset:53760
	v_pk_add_f32 v[58:59], v[40:41], v[48:49] neg_lo:[0,1] neg_hi:[0,1]
	v_fmac_f32_e32 v51, v50, v19
	v_sub_f32_e32 v50, v120, v119
	v_fmac_f32_e32 v51, v58, v114
	v_fma_f32 v50, v50, v1, v119
	v_sub_f32_e32 v58, v118, v119
	v_fmac_f32_e32 v50, v58, v21
	v_div_scale_f32 v58, s[12:13], v56, v56, s39
	v_fmac_f32_e32 v60, v59, v115
	v_rcp_f32_e32 v59, v58
	v_cvt_pk_bf16_f32 v50, v50, s0
	ds_write_b16 v109, v50 offset:33792
	v_pk_add_f32 v[48:49], v[48:49], v[40:41] neg_lo:[0,1] neg_hi:[0,1]
	v_fma_f32 v61, -v58, v59, 1.0
	v_fmac_f32_e32 v59, v61, v59
	v_div_scale_f32 v61, vcc, s39, v56, s39
	v_mul_f32_e32 v62, v61, v59
	v_fma_f32 v63, -v58, v62, v61
	v_fmac_f32_e32 v62, v63, v59
	v_fma_f32 v58, -v58, v62, v61
	v_div_fmas_f32 v58, v58, v59, v62
	v_div_fixup_f32 v56, v58, v56, s39
	v_div_scale_f32 v58, s[12:13], v54, v54, s39
	v_rcp_f32_e32 v59, v58
	v_mul_f32_e32 v56, 0x3fb8aa3b, v56
	v_exp_f32_e32 v56, v56
	v_fma_f32 v61, -v58, v59, 1.0
	v_fmac_f32_e32 v59, v61, v59
	v_div_scale_f32 v61, vcc, s39, v54, s39
	v_mul_f32_e32 v62, v61, v59
	v_fma_f32 v63, -v58, v62, v61
	v_fmac_f32_e32 v62, v63, v59
	v_fma_f32 v58, -v58, v62, v61
	v_div_fmas_f32 v58, v58, v59, v62
	v_div_fixup_f32 v54, v58, v54, s39
	v_div_scale_f32 v58, s[12:13], v52, v52, 1.0
	v_rcp_f32_e32 v59, v58
	v_mul_f32_e32 v54, 0x3fb8aa3b, v54
	v_exp_f32_e32 v54, v54
	v_sub_f32_e32 v56, 1.0, v56
	v_fma_f32 v61, -v58, v59, 1.0
	v_fmac_f32_e32 v59, v61, v59
	v_div_scale_f32 v61, vcc, 1.0, v52, 1.0
	v_mul_f32_e32 v62, v61, v59
	v_fma_f32 v63, -v58, v62, v61
	v_fmac_f32_e32 v62, v63, v59
	v_fma_f32 v58, -v58, v62, v61
	v_div_fmas_f32 v58, v58, v59, v62
	v_div_fixup_f32 v52, v58, v52, 1.0
	v_mul_f32_e32 v58, v5, v51
	v_mul_f32_e32 v59, v58, v58
	v_sub_f32_e32 v54, 1.0, v54
	s_nop 0
	v_mov_b32_dpp v59, v59 quad_perm:[1,0,3,2] row_mask:0xf bank_mask:0xf bound_ctrl:1
	v_fmac_f32_e32 v59, v58, v58
	s_nop 1
	v_add_f32_dpp v59, v59, v59 quad_perm:[2,3,0,1] row_mask:0xf bank_mask:0xf bound_ctrl:1
	s_nop 1
	v_add_f32_dpp v59, v59, v59 row_half_mirror row_mask:0xf bank_mask:0xf bound_ctrl:1
	s_nop 1
	v_add_f32_dpp v59, v59, v59 row_mirror row_mask:0xf bank_mask:0xf bound_ctrl:1
	s_nop 0
	v_readlane_b32 s13, v59, 16
	v_readlane_b32 s12, v59, 0
	s_nop 0
	v_mov_b32_e32 v61, s13
	v_readlane_b32 s13, v59, 48
	v_add_f32_e32 v61, s12, v61
	v_readlane_b32 s12, v59, 32
	v_mov_b32_e32 v59, s13
	s_nop 0
	v_add_f32_e32 v59, s12, v59
	v_add_f32_e32 v59, v61, v59
	v_max_f32_e32 v59, 0x179abe15, v59
	v_rsq_f32_e32 v59, v59
	s_nop 0
	v_mul_f32_e32 v58, v58, v59
	v_add_f32_e32 v59, -1.0, v52
	v_mul_f32_e32 v52, v52, v58
	v_cvt_pk_bf16_f32 v50, -v58, s0
	v_fma_f32 v59, v3, v59, 1.0
	ds_write_b16 v109, v50 offset:41984
	v_cvt_pk_bf16_f32 v50, v52, s0
	v_mul_f32_e32 v51, v51, v59
	ds_write_b16 v109, v50 offset:50176
	v_cvt_pk_bf16_f32 v50, v56, s0
	v_mov_b32_e32 v52, v41
	v_cvt_pk_bf16_f32 v51, v51, s0
	ds_write_b16 v109, v50 offset:58368
	v_cvt_pk_bf16_f32 v50, v54, s0
	v_fmac_f32_e32 v52, v49, v23
	v_mov_b32_e32 v49, v40
	ds_write_b16 v109, v51 offset:25600
	ds_write_b16 v108, v50 offset:54272
	v_pk_add_f32 v[50:51], v[38:39], v[40:41] neg_lo:[0,1] neg_hi:[0,1]
	v_fmac_f32_e32 v49, v48, v19
	v_sub_f32_e32 v48, v119, v118
	v_fmac_f32_e32 v49, v50, v114
	v_fma_f32 v48, v48, v1, v118
	v_sub_f32_e32 v50, v117, v118
	v_fmac_f32_e32 v48, v50, v21
	v_add_f32_e32 v50, v11, v57
	v_mul_f32_e32 v50, 0xbfb8aa3b, v50
	v_exp_f32_e32 v50, v50
	v_fmac_f32_e32 v52, v51, v115
	v_cvt_pk_bf16_f32 v48, v48, s0
	ds_write_b16 v109, v48 offset:34304
	v_add_f32_e32 v50, 1.0, v50
	v_div_scale_f32 v51, s[12:13], v50, v50, s39
	v_rcp_f32_e32 v54, v51
	v_pk_add_f32 v[40:41], v[40:41], v[38:39] neg_lo:[0,1] neg_hi:[0,1]
	v_cvt_pk_bf16_f32 v52, v52, s0
	ds_write_b16 v109, v52 offset:17920
	v_fma_f32 v56, -v51, v54, 1.0
	v_fmac_f32_e32 v54, v56, v54
	v_div_scale_f32 v56, vcc, s39, v50, s39
	v_mul_f32_e32 v57, v56, v54
	v_fma_f32 v58, -v51, v57, v56
	v_fmac_f32_e32 v57, v58, v54
	v_fma_f32 v51, -v51, v57, v56
	v_div_fmas_f32 v51, v51, v54, v57
	v_div_fixup_f32 v50, v51, v50, s39
	v_add_f32_e32 v51, v9, v55
	v_mul_f32_e32 v51, 0xbfb8aa3b, v51
	v_exp_f32_e32 v51, v51
	v_mul_f32_e32 v50, 0x3fb8aa3b, v50
	v_exp_f32_e32 v50, v50
	v_cvt_pk_bf16_f32 v59, v60, s0
	v_add_f32_e32 v51, 1.0, v51
	v_div_scale_f32 v54, s[12:13], v51, v51, s39
	v_rcp_f32_e32 v55, v54
	v_sub_f32_e32 v50, 1.0, v50
	ds_write_b16 v109, v59 offset:17408
	v_fma_f32 v56, -v54, v55, 1.0
	v_fmac_f32_e32 v55, v56, v55
	v_div_scale_f32 v56, vcc, s39, v51, s39
	v_mul_f32_e32 v57, v56, v55
	v_fma_f32 v58, -v54, v57, v56
	v_fmac_f32_e32 v57, v58, v55
	v_fma_f32 v54, -v54, v57, v56
	v_div_fmas_f32 v54, v54, v55, v57
	v_div_fixup_f32 v51, v54, v51, s39
	v_div_scale_f32 v54, s[12:13], v53, v53, 1.0
	v_rcp_f32_e32 v55, v54
	v_mul_f32_e32 v51, 0x3fb8aa3b, v51
	v_exp_f32_e32 v51, v51
	v_fma_f32 v56, -v54, v55, 1.0
	v_fmac_f32_e32 v55, v56, v55
	v_div_scale_f32 v56, vcc, 1.0, v53, 1.0
	v_mul_f32_e32 v57, v56, v55
	v_fma_f32 v58, -v54, v57, v56
	v_fmac_f32_e32 v57, v58, v55
	v_fma_f32 v54, -v54, v57, v56
	v_div_fmas_f32 v54, v54, v55, v57
	v_div_fixup_f32 v53, v54, v53, 1.0
	v_mul_f32_e32 v54, v5, v49
	v_mul_f32_e32 v55, v54, v54
	v_sub_f32_e32 v51, 1.0, v51
	s_nop 0
	v_mov_b32_dpp v55, v55 quad_perm:[1,0,3,2] row_mask:0xf bank_mask:0xf bound_ctrl:1
	v_fmac_f32_e32 v55, v54, v54
	s_nop 1
	v_add_f32_dpp v55, v55, v55 quad_perm:[2,3,0,1] row_mask:0xf bank_mask:0xf bound_ctrl:1
	s_nop 1
	v_add_f32_dpp v55, v55, v55 row_half_mirror row_mask:0xf bank_mask:0xf bound_ctrl:1
	s_nop 1
	v_add_f32_dpp v55, v55, v55 row_mirror row_mask:0xf bank_mask:0xf bound_ctrl:1
	s_nop 0
	v_readlane_b32 s13, v55, 16
	v_readlane_b32 s12, v55, 0
	s_nop 0
	v_mov_b32_e32 v56, s13
	v_readlane_b32 s13, v55, 48
	v_add_f32_e32 v56, s12, v56
	v_readlane_b32 s12, v55, 32
	v_mov_b32_e32 v55, s13
	s_nop 0
	v_add_f32_e32 v55, s12, v55
	v_add_f32_e32 v55, v56, v55
	v_max_f32_e32 v55, 0x179abe15, v55
	v_rsq_f32_e32 v55, v55
	s_nop 0
	v_mul_f32_e32 v54, v54, v55
	v_add_f32_e32 v55, -1.0, v53
	v_mul_f32_e32 v53, v53, v54
	v_cvt_pk_bf16_f32 v48, -v54, s0
	v_fma_f32 v55, v3, v55, 1.0
	ds_write_b16 v109, v48 offset:42496
	v_cvt_pk_bf16_f32 v48, v53, s0
	v_mul_f32_e32 v49, v49, v55
	ds_write_b16 v109, v48 offset:50688
	v_cvt_pk_bf16_f32 v48, v50, s0
	v_mov_b32_e32 v50, v39
	v_cvt_pk_bf16_f32 v49, v49, s0
	ds_write_b16 v109, v48 offset:58880
	v_cvt_pk_bf16_f32 v48, v51, s0
	v_fmac_f32_e32 v50, v41, v23
	v_mov_b32_e32 v41, v38
	ds_write_b16 v109, v49 offset:26112
	ds_write_b16 v108, v48 offset:54784
	v_pk_add_f32 v[48:49], v[32:33], v[38:39] neg_lo:[0,1] neg_hi:[0,1]
	v_fmac_f32_e32 v41, v40, v19
	v_sub_f32_e32 v40, v118, v117
	v_fmac_f32_e32 v41, v48, v114
	v_fma_f32 v40, v40, v1, v117
	v_sub_f32_e32 v48, v116, v117
	v_fmac_f32_e32 v40, v48, v21
	v_div_scale_f32 v48, s[12:13], v46, v46, s39
	v_fmac_f32_e32 v50, v49, v115
	v_rcp_f32_e32 v49, v48
	v_cvt_pk_bf16_f32 v40, v40, s0
	ds_write_b16 v109, v40 offset:34816
	v_pk_add_f32 v[38:39], v[38:39], v[32:33] neg_lo:[0,1] neg_hi:[0,1]
	v_fma_f32 v51, -v48, v49, 1.0
	v_fmac_f32_e32 v49, v51, v49
	v_div_scale_f32 v51, vcc, s39, v46, s39
	v_mul_f32_e32 v52, v51, v49
	v_fma_f32 v53, -v48, v52, v51
	v_fmac_f32_e32 v52, v53, v49
	v_fma_f32 v48, -v48, v52, v51
	v_div_fmas_f32 v48, v48, v49, v52
	v_div_fixup_f32 v46, v48, v46, s39
	v_div_scale_f32 v48, s[12:13], v44, v44, s39
	v_rcp_f32_e32 v49, v48
	v_mul_f32_e32 v46, 0x3fb8aa3b, v46
	v_exp_f32_e32 v46, v46
	v_fma_f32 v51, -v48, v49, 1.0
	v_fmac_f32_e32 v49, v51, v49
	v_div_scale_f32 v51, vcc, s39, v44, s39
	v_mul_f32_e32 v52, v51, v49
	v_fma_f32 v53, -v48, v52, v51
	v_fmac_f32_e32 v52, v53, v49
	v_fma_f32 v48, -v48, v52, v51
	v_div_fmas_f32 v48, v48, v49, v52
	v_div_fixup_f32 v44, v48, v44, s39
	v_div_scale_f32 v48, s[12:13], v42, v42, 1.0
	v_rcp_f32_e32 v49, v48
	v_mul_f32_e32 v44, 0x3fb8aa3b, v44
	v_exp_f32_e32 v44, v44
	v_sub_f32_e32 v46, 1.0, v46
	v_fma_f32 v51, -v48, v49, 1.0
	v_fmac_f32_e32 v49, v51, v49
	v_div_scale_f32 v51, vcc, 1.0, v42, 1.0
	v_mul_f32_e32 v52, v51, v49
	v_fma_f32 v53, -v48, v52, v51
	v_fmac_f32_e32 v52, v53, v49
	v_fma_f32 v48, -v48, v52, v51
	v_div_fmas_f32 v48, v48, v49, v52
	v_div_fixup_f32 v42, v48, v42, 1.0
	v_mul_f32_e32 v48, v5, v41
	v_mul_f32_e32 v49, v48, v48
	v_sub_f32_e32 v44, 1.0, v44
	s_nop 0
	v_mov_b32_dpp v49, v49 quad_perm:[1,0,3,2] row_mask:0xf bank_mask:0xf bound_ctrl:1
	v_fmac_f32_e32 v49, v48, v48
	s_nop 1
	v_add_f32_dpp v49, v49, v49 quad_perm:[2,3,0,1] row_mask:0xf bank_mask:0xf bound_ctrl:1
	s_nop 1
	v_add_f32_dpp v49, v49, v49 row_half_mirror row_mask:0xf bank_mask:0xf bound_ctrl:1
	s_nop 1
	v_add_f32_dpp v49, v49, v49 row_mirror row_mask:0xf bank_mask:0xf bound_ctrl:1
	s_nop 0
	v_readlane_b32 s13, v49, 16
	v_readlane_b32 s12, v49, 0
	s_nop 0
	v_mov_b32_e32 v51, s13
	v_readlane_b32 s13, v49, 48
	v_add_f32_e32 v51, s12, v51
	v_readlane_b32 s12, v49, 32
	v_mov_b32_e32 v49, s13
	s_nop 0
	v_add_f32_e32 v49, s12, v49
	v_add_f32_e32 v49, v51, v49
	v_max_f32_e32 v49, 0x179abe15, v49
	v_rsq_f32_e32 v49, v49
	s_nop 0
	v_mul_f32_e32 v48, v48, v49
	v_add_f32_e32 v49, -1.0, v42
	v_mul_f32_e32 v42, v42, v48
	v_cvt_pk_bf16_f32 v40, -v48, s0
	v_fma_f32 v49, v3, v49, 1.0
	ds_write_b16 v109, v40 offset:43008
	v_cvt_pk_bf16_f32 v40, v42, s0
	v_mul_f32_e32 v41, v41, v49
	ds_write_b16 v109, v40 offset:51200
	v_cvt_pk_bf16_f32 v40, v46, s0
	v_mov_b32_e32 v42, v33
	v_cvt_pk_bf16_f32 v41, v41, s0
	ds_write_b16 v109, v40 offset:59392
	v_cvt_pk_bf16_f32 v40, v44, s0
	v_fmac_f32_e32 v42, v39, v23
	v_mov_b32_e32 v39, v32
	ds_write_b16 v109, v41 offset:26624
	ds_write_b16 v108, v40 offset:55296
	v_pk_add_f32 v[40:41], v[26:27], v[32:33] neg_lo:[0,1] neg_hi:[0,1]
	v_fmac_f32_e32 v39, v38, v19
	v_sub_f32_e32 v38, v117, v116
	v_fmac_f32_e32 v39, v40, v114
	v_fma_f32 v38, v38, v1, v116
	v_sub_f32_e32 v40, v15, v116
	v_fmac_f32_e32 v38, v40, v21
	v_add_f32_e32 v40, v11, v47
	v_mul_f32_e32 v40, 0xbfb8aa3b, v40
	v_exp_f32_e32 v40, v40
	v_fmac_f32_e32 v42, v41, v115
	v_cvt_pk_bf16_f32 v38, v38, s0
	ds_write_b16 v109, v38 offset:35328
	v_add_f32_e32 v40, 1.0, v40
	v_div_scale_f32 v41, s[12:13], v40, v40, s39
	v_rcp_f32_e32 v44, v41
	v_pk_add_f32 v[32:33], v[32:33], v[26:27] neg_lo:[0,1] neg_hi:[0,1]
	v_cvt_pk_bf16_f32 v42, v42, s0
	ds_write_b16 v109, v42 offset:18944
	v_fma_f32 v46, -v41, v44, 1.0
	v_fmac_f32_e32 v44, v46, v44
	v_div_scale_f32 v46, vcc, s39, v40, s39
	v_mul_f32_e32 v47, v46, v44
	v_fma_f32 v48, -v41, v47, v46
	v_fmac_f32_e32 v47, v48, v44
	v_fma_f32 v41, -v41, v47, v46
	v_div_fmas_f32 v41, v41, v44, v47
	v_div_fixup_f32 v40, v41, v40, s39
	v_add_f32_e32 v41, v9, v45
	v_mul_f32_e32 v41, 0xbfb8aa3b, v41
	v_exp_f32_e32 v41, v41
	v_mul_f32_e32 v40, 0x3fb8aa3b, v40
	v_exp_f32_e32 v40, v40
	v_add_f32_e32 v9, v9, v35
	v_add_f32_e32 v41, 1.0, v41
	v_div_scale_f32 v44, s[12:13], v41, v41, s39
	v_rcp_f32_e32 v45, v44
	v_sub_f32_e32 v40, 1.0, v40
	v_mul_f32_e32 v9, 0xbfb8aa3b, v9
	v_exp_f32_e32 v9, v9
	v_fma_f32 v46, -v44, v45, 1.0
	v_fmac_f32_e32 v45, v46, v45
	v_div_scale_f32 v46, vcc, s39, v41, s39
	v_mul_f32_e32 v47, v46, v45
	v_fma_f32 v48, -v44, v47, v46
	v_fmac_f32_e32 v47, v48, v45
	v_fma_f32 v44, -v44, v47, v46
	v_div_fmas_f32 v44, v44, v45, v47
	v_div_fixup_f32 v41, v44, v41, s39
	v_div_scale_f32 v44, s[12:13], v43, v43, 1.0
	v_rcp_f32_e32 v45, v44
	v_mul_f32_e32 v41, 0x3fb8aa3b, v41
	v_exp_f32_e32 v41, v41
	v_add_f32_e32 v9, 1.0, v9
	v_fma_f32 v46, -v44, v45, 1.0
	v_fmac_f32_e32 v45, v46, v45
	v_div_scale_f32 v46, vcc, 1.0, v43, 1.0
	v_mul_f32_e32 v47, v46, v45
	v_fma_f32 v48, -v44, v47, v46
	v_fmac_f32_e32 v47, v48, v45
	v_fma_f32 v44, -v44, v47, v46
	v_div_fmas_f32 v44, v44, v45, v47
	v_div_fixup_f32 v43, v44, v43, 1.0
	v_mul_f32_e32 v44, v5, v39
	v_mul_f32_e32 v45, v44, v44
	v_sub_f32_e32 v41, 1.0, v41
	v_cvt_pk_bf16_f32 v49, v50, s0
	v_mov_b32_dpp v45, v45 quad_perm:[1,0,3,2] row_mask:0xf bank_mask:0xf bound_ctrl:1
	v_fmac_f32_e32 v45, v44, v44
	ds_write_b16 v109, v49 offset:18432
	s_nop 0
	v_add_f32_dpp v45, v45, v45 quad_perm:[2,3,0,1] row_mask:0xf bank_mask:0xf bound_ctrl:1
	s_nop 1
	v_add_f32_dpp v45, v45, v45 row_half_mirror row_mask:0xf bank_mask:0xf bound_ctrl:1
	s_nop 1
	v_add_f32_dpp v45, v45, v45 row_mirror row_mask:0xf bank_mask:0xf bound_ctrl:1
	s_nop 0
	v_readlane_b32 s13, v45, 16
	v_readlane_b32 s12, v45, 0
	s_nop 0
	v_mov_b32_e32 v46, s13
	v_readlane_b32 s13, v45, 48
	v_add_f32_e32 v46, s12, v46
	v_readlane_b32 s12, v45, 32
	v_mov_b32_e32 v45, s13
	s_nop 0
	v_add_f32_e32 v45, s12, v45
	v_add_f32_e32 v45, v46, v45
	v_max_f32_e32 v45, 0x179abe15, v45
	v_rsq_f32_e32 v45, v45
	s_nop 0
	v_mul_f32_e32 v44, v44, v45
	v_add_f32_e32 v45, -1.0, v43
	v_mul_f32_e32 v43, v43, v44
	v_cvt_pk_bf16_f32 v38, -v44, s0
	v_fma_f32 v45, v3, v45, 1.0
	ds_write_b16 v109, v38 offset:43520
	v_cvt_pk_bf16_f32 v38, v43, s0
	v_mul_f32_e32 v39, v39, v45
	ds_write_b16 v109, v38 offset:51712
	v_cvt_pk_bf16_f32 v38, v40, s0
	v_mov_b32_e32 v40, v27
	v_cvt_pk_bf16_f32 v39, v39, s0
	ds_write_b16 v109, v38 offset:59904
	v_cvt_pk_bf16_f32 v38, v41, s0
	v_fmac_f32_e32 v40, v33, v23
	v_mov_b32_e32 v33, v26
	ds_write_b16 v109, v39 offset:27136
	ds_write_b16 v108, v38 offset:55808
	v_pk_add_f32 v[38:39], v[24:25], v[26:27] neg_lo:[0,1] neg_hi:[0,1]
	v_fmac_f32_e32 v33, v32, v19
	v_sub_f32_e32 v32, v116, v15
	v_fmac_f32_e32 v33, v38, v114
	v_fma_f32 v32, v32, v1, v15
	v_sub_f32_e32 v38, v13, v15
	v_fmac_f32_e32 v32, v38, v21
	v_div_scale_f32 v38, s[12:13], v36, v36, s39
	v_fmac_f32_e32 v40, v39, v115
	v_rcp_f32_e32 v39, v38
	v_sub_f32_e32 v15, v15, v13
	v_fmac_f32_e32 v13, v15, v1
	v_add_f32_e32 v1, v11, v37
	v_fma_f32 v41, -v38, v39, 1.0
	v_fmac_f32_e32 v39, v41, v39
	v_div_scale_f32 v41, vcc, s39, v36, s39
	v_mul_f32_e32 v42, v41, v39
	v_fma_f32 v43, -v38, v42, v41
	v_fmac_f32_e32 v42, v43, v39
	v_fma_f32 v38, -v38, v42, v41
	v_div_fmas_f32 v38, v38, v39, v42
	v_div_fixup_f32 v36, v38, v36, s39
	v_div_scale_f32 v38, s[12:13], v34, v34, s39
	v_rcp_f32_e32 v39, v38
	v_mul_f32_e32 v1, 0xbfb8aa3b, v1
	v_exp_f32_e32 v1, v1
	v_fmac_f32_e32 v13, v17, v21
	v_fma_f32 v41, -v38, v39, 1.0
	v_fmac_f32_e32 v39, v41, v39
	v_div_scale_f32 v41, vcc, s39, v34, s39
	v_mul_f32_e32 v42, v41, v39
	v_fma_f32 v43, -v38, v42, v41
	v_fmac_f32_e32 v42, v43, v39
	v_fma_f32 v38, -v38, v42, v41
	v_div_fmas_f32 v38, v38, v39, v42
	v_div_fixup_f32 v34, v38, v34, s39
	v_div_scale_f32 v38, s[12:13], v30, v30, 1.0
	v_rcp_f32_e32 v39, v38
	v_add_f32_e32 v1, 1.0, v1
	v_pk_add_f32 v[26:27], v[26:27], v[24:25] neg_lo:[0,1] neg_hi:[0,1]
	v_mul_f32_e32 v36, 0x3fb8aa3b, v36
	v_fma_f32 v41, -v38, v39, 1.0
	v_fmac_f32_e32 v39, v41, v39
	v_div_scale_f32 v41, vcc, 1.0, v30, 1.0
	v_mul_f32_e32 v42, v41, v39
	v_fma_f32 v43, -v38, v42, v41
	v_fmac_f32_e32 v42, v43, v39
	v_fma_f32 v38, -v38, v42, v41
	v_div_fmas_f32 v38, v38, v39, v42
	v_div_fixup_f32 v30, v38, v30, 1.0
	v_mul_f32_e32 v38, v5, v33
	v_mul_f32_e32 v39, v38, v38
	v_fmac_f32_e32 v24, v26, v19
	v_fmac_f32_e32 v24, v28, v114
	v_mov_b32_dpp v39, v39 quad_perm:[1,0,3,2] row_mask:0xf bank_mask:0xf bound_ctrl:1
	v_fmac_f32_e32 v39, v38, v38
	v_mul_f32_e32 v5, v5, v24
	v_exp_f32_e32 v36, v36
	v_add_f32_dpp v39, v39, v39 quad_perm:[2,3,0,1] row_mask:0xf bank_mask:0xf bound_ctrl:1
	v_mul_f32_e32 v34, 0x3fb8aa3b, v34
	v_exp_f32_e32 v34, v34
	v_add_f32_dpp v39, v39, v39 row_half_mirror row_mask:0xf bank_mask:0xf bound_ctrl:1
	v_sub_f32_e32 v36, 1.0, v36
	v_cvt_pk_bf16_f32 v32, v32, s0
	v_add_f32_dpp v39, v39, v39 row_mirror row_mask:0xf bank_mask:0xf bound_ctrl:1
	v_sub_f32_e32 v34, 1.0, v34
	v_readlane_b32 s13, v39, 16
	v_readlane_b32 s12, v39, 0
	ds_write_b16 v109, v32 offset:35840
	v_mov_b32_e32 v41, s13
	v_readlane_b32 s13, v39, 48
	v_add_f32_e32 v41, s12, v41
	v_readlane_b32 s12, v39, 32
	v_mov_b32_e32 v39, s13
	s_nop 0
	v_add_f32_e32 v39, s12, v39
	v_div_scale_f32 v11, s[12:13], v1, v1, s39
	v_rcp_f32_e32 v15, v11
	v_add_f32_e32 v39, v41, v39
	v_max_f32_e32 v39, 0x179abe15, v39
	v_rsq_f32_e32 v39, v39
	v_fma_f32 v17, -v11, v15, 1.0
	v_fmac_f32_e32 v15, v17, v15
	v_div_scale_f32 v17, vcc, s39, v1, s39
	v_mul_f32_e32 v19, v17, v15
	v_fma_f32 v21, -v11, v19, v17
	v_fmac_f32_e32 v19, v21, v15
	v_fma_f32 v11, -v11, v19, v17
	v_div_fmas_f32 v11, v11, v15, v19
	v_div_fixup_f32 v1, v11, v1, s39
	v_div_scale_f32 v11, s[12:13], v9, v9, s39
	v_rcp_f32_e32 v15, v11
	v_mul_f32_e32 v38, v38, v39
	v_mul_f32_e32 v1, 0x3fb8aa3b, v1
	v_add_f32_e32 v39, -1.0, v30
	v_fma_f32 v17, -v11, v15, 1.0
	v_fmac_f32_e32 v15, v17, v15
	v_div_scale_f32 v17, vcc, s39, v9, s39
	v_mul_f32_e32 v19, v17, v15
	v_fma_f32 v21, -v11, v19, v17
	v_fmac_f32_e32 v19, v21, v15
	v_fma_f32 v11, -v11, v19, v17
	v_div_fmas_f32 v11, v11, v15, v19
	v_div_fixup_f32 v9, v11, v9, s39
	v_div_scale_f32 v11, s[12:13], v7, v7, 1.0
	v_rcp_f32_e32 v15, v11
	v_mul_f32_e32 v30, v30, v38
	v_exp_f32_e32 v1, v1
	v_mul_f32_e32 v9, 0x3fb8aa3b, v9
	v_fma_f32 v17, -v11, v15, 1.0
	v_fmac_f32_e32 v15, v17, v15
	v_div_scale_f32 v17, vcc, 1.0, v7, 1.0
	v_mul_f32_e32 v19, v17, v15
	v_fma_f32 v21, -v11, v19, v17
	v_fmac_f32_e32 v19, v21, v15
	v_fma_f32 v11, -v11, v19, v17
	v_div_fmas_f32 v11, v11, v15, v19
	v_div_fixup_f32 v7, v11, v7, 1.0
	v_mul_f32_e32 v11, v5, v5
	v_fma_f32 v39, v3, v39, 1.0
	v_cvt_pk_bf16_f32 v30, v30, s0
	v_mov_b32_dpp v11, v11 quad_perm:[1,0,3,2] row_mask:0xf bank_mask:0xf bound_ctrl:1
	v_fmac_f32_e32 v11, v5, v5
	v_exp_f32_e32 v9, v9
	ds_write_b16 v109, v30 offset:52224
	v_add_f32_dpp v11, v11, v11 quad_perm:[2,3,0,1] row_mask:0xf bank_mask:0xf bound_ctrl:1
	v_cvt_pk_bf16_f32 v30, v36, s0
	ds_write_b16 v109, v30 offset:60416
	v_add_f32_dpp v11, v11, v11 row_half_mirror row_mask:0xf bank_mask:0xf bound_ctrl:1
	v_cvt_pk_bf16_f32 v30, v34, s0
	ds_write_b16 v108, v30 offset:56320
	v_add_f32_dpp v11, v11, v11 row_mirror row_mask:0xf bank_mask:0xf bound_ctrl:1
	v_mov_b32_e32 v30, v25
	v_readlane_b32 s13, v11, 16
	v_readlane_b32 s12, v11, 0
	v_sub_f32_e32 v1, 1.0, v1
	v_mov_b32_e32 v15, s13
	v_readlane_b32 s13, v11, 48
	v_add_f32_e32 v15, s12, v15
	v_readlane_b32 s12, v11, 32
	v_mov_b32_e32 v11, s13
	v_fmac_f32_e32 v30, v27, v23
	v_add_f32_e32 v11, s12, v11
	v_add_f32_e32 v11, v15, v11
	v_max_f32_e32 v11, 0x179abe15, v11
	v_rsq_f32_e32 v11, v11
	v_sub_f32_e32 v9, 1.0, v9
	v_cvt_pk_bf16_f32 v1, v1, s0
	v_fmac_f32_e32 v30, v29, v115
	v_mul_f32_e32 v5, v5, v11
	v_add_f32_e32 v11, -1.0, v7
	v_fma_f32 v3, v3, v11, 1.0
	v_mul_f32_e32 v3, v24, v3
	v_cvt_pk_bf16_f32 v3, v3, s0
	ds_write_b16 v109, v3 offset:28160
	v_cvt_pk_bf16_f32 v3, v13, s0
	v_mul_f32_e32 v7, v7, v5
	ds_write_b16 v109, v3 offset:36352
	v_cvt_pk_bf16_f32 v3, -v5, s0
	ds_write_b16 v109, v3 offset:44544
	v_cvt_pk_bf16_f32 v3, v7, s0
	ds_write_b16 v109, v1 offset:60928
	v_cvt_pk_bf16_f32 v1, v9, s0
	v_cvt_pk_bf16_f32 v11, v30, s0
	ds_write_b16 v109, v3 offset:52736
	ds_write_b16 v108, v1 offset:56832
	v_ashrrev_i32_e32 v1, 9, v0
	v_bfe_u32 v3, v0, 5, 4
	v_lshlrev_b32_e32 v7, 4, v0
	v_mul_f32_e32 v33, v33, v39
	ds_write_b16 v109, v11 offset:19968
	v_lshl_add_u32 v5, v1, 13, 16
	v_lshlrev_b32_e32 v11, 9, v3
	v_and_b32_e32 v176, 0x1f0, v7
	v_cvt_pk_bf16_f32 v39, v40, s0
	v_cvt_pk_bf16_f32 v33, v33, s0
	v_cvt_pk_bf16_f32 v32, -v38, s0
	v_add3_u32 v5, v5, v11, v176
	ds_write_b16 v109, v39 offset:19456
	ds_write_b16 v109, v33 offset:27648
	ds_write_b16 v109, v32 offset:44032
	s_waitcnt lgkmcnt(0)
	s_barrier
	ds_read_b128 v[24:27], v5 offset:12288
	v_or_b32_e32 v32, s20, v3
	v_mov_b64_e32 v[28:29], s[80:81]
	v_ashrrev_i32_e32 v33, 31, v32
	v_mad_i64_i32 v[30:31], s[12:13], v1, s40, v[28:29]
	v_lshlrev_b64 v[32:33], 9, v[32:33]
	v_ashrrev_i32_e32 v1, 9, v2
	v_bfe_u32 v5, v2, 5, 4
	v_lshl_add_u64 v[30:31], v[30:31], 0, v[32:33]
	v_lshl_add_u32 v2, v1, 13, 16
	v_lshlrev_b32_e32 v3, 9, v5
	v_lshl_add_u64 v[30:31], v[30:31], 0, v[176:177]
	v_add3_u32 v2, v2, v3, v176
	s_waitcnt lgkmcnt(0)
	global_store_dwordx4 v[30:31], v[24:27], off
	ds_read_b128 v[24:27], v2 offset:12288
	v_or_b32_e32 v30, s20, v5
	v_ashrrev_i32_e32 v31, 31, v30
	v_mad_i64_i32 v[2:3], s[12:13], v1, s40, v[28:29]
	v_lshlrev_b64 v[30:31], 9, v[30:31]
	v_lshl_add_u64 v[2:3], v[2:3], 0, v[30:31]
	v_lshl_add_u64 v[2:3], v[2:3], 0, v[176:177]
	v_ashrrev_i32_e32 v1, 9, v4
	s_waitcnt lgkmcnt(0)
	global_store_dwordx4 v[2:3], v[24:27], off
	v_lshl_add_u32 v2, v1, 13, 16
	v_add3_u32 v2, v2, v11, v176
	ds_read_b128 v[2:5], v2 offset:12288
	v_mad_i64_i32 v[24:25], s[12:13], v1, s40, v[28:29]
	v_lshl_add_u64 v[24:25], v[24:25], 0, v[32:33]
	v_lshl_add_u64 v[24:25], v[24:25], 0, v[176:177]
	v_ashrrev_i32_e32 v1, 9, v6
	v_bfe_u32 v9, v6, 5, 4
	s_waitcnt lgkmcnt(0)
	global_store_dwordx4 v[24:25], v[2:5], off
	v_or_b32_e32 v24, s20, v9
	v_ashrrev_i32_e32 v25, 31, v24
	v_lshl_add_u32 v2, v1, 13, 16
	v_lshlrev_b32_e32 v3, 9, v9
	v_add3_u32 v2, v2, v3, v176
	ds_read_b128 v[2:5], v2 offset:12288
	v_mad_i64_i32 v[6:7], s[12:13], v1, s40, v[28:29]
	v_lshlrev_b64 v[24:25], 9, v[24:25]
	v_lshl_add_u64 v[6:7], v[6:7], 0, v[24:25]
	v_lshl_add_u64 v[6:7], v[6:7], 0, v[176:177]
	v_ashrrev_i32_e32 v1, 9, v8
	s_waitcnt lgkmcnt(0)
	global_store_dwordx4 v[6:7], v[2:5], off
	v_mad_i64_i32 v[6:7], s[12:13], v1, s40, v[28:29]
	s_nop 0
	v_lshl_add_u32 v2, v1, 13, 16
	v_add3_u32 v2, v2, v11, v176
	ds_read_b128 v[2:5], v2 offset:12288
	v_lshl_add_u64 v[6:7], v[6:7], 0, v[32:33]
	v_lshl_add_u64 v[6:7], v[6:7], 0, v[176:177]
	v_ashrrev_i32_e32 v1, 9, v10
	v_bfe_u32 v8, v10, 5, 4
	s_waitcnt lgkmcnt(0)
	global_store_dwordx4 v[6:7], v[2:5], off
	v_mad_i64_i32 v[6:7], s[12:13], v1, s40, v[28:29]
	s_nop 0
	v_lshl_add_u32 v2, v1, 13, 16
	v_lshlrev_b32_e32 v3, 9, v8
	v_add3_u32 v2, v2, v3, v176
	ds_read_b128 v[2:5], v2 offset:12288
	v_or_b32_e32 v8, s20, v8
	v_ashrrev_i32_e32 v9, 31, v8
	v_lshlrev_b64 v[8:9], 9, v[8:9]
	v_lshl_add_u64 v[6:7], v[6:7], 0, v[8:9]
	v_lshl_add_u64 v[6:7], v[6:7], 0, v[176:177]
	v_ashrrev_i32_e32 v1, 9, v12
	s_waitcnt lgkmcnt(0)
	global_store_dwordx4 v[6:7], v[2:5], off
	v_mad_i64_i32 v[6:7], s[12:13], v1, s40, v[28:29]
	s_nop 0
	v_lshl_add_u32 v2, v1, 13, 16
	v_add3_u32 v2, v2, v11, v176
	ds_read_b128 v[2:5], v2 offset:12288
	v_lshl_add_u64 v[6:7], v[6:7], 0, v[32:33]
	v_lshl_add_u64 v[6:7], v[6:7], 0, v[176:177]
	v_ashrrev_i32_e32 v1, 9, v14
	v_bfe_u32 v8, v14, 5, 4
	s_waitcnt lgkmcnt(0)
	global_store_dwordx4 v[6:7], v[2:5], off
	v_mad_i64_i32 v[6:7], s[12:13], v1, s40, v[28:29]
	s_nop 0
	v_lshl_add_u32 v2, v1, 13, 16
	v_lshlrev_b32_e32 v3, 9, v8
	v_add3_u32 v2, v2, v3, v176
	ds_read_b128 v[2:5], v2 offset:12288
	v_or_b32_e32 v8, s20, v8
	v_ashrrev_i32_e32 v9, 31, v8
	v_lshlrev_b64 v[8:9], 9, v[8:9]
	v_lshl_add_u64 v[6:7], v[6:7], 0, v[8:9]
	v_lshl_add_u64 v[6:7], v[6:7], 0, v[176:177]
	v_ashrrev_i32_e32 v1, 9, v16
	s_waitcnt lgkmcnt(0)
	global_store_dwordx4 v[6:7], v[2:5], off
	v_mad_i64_i32 v[6:7], s[12:13], v1, s40, v[28:29]
	s_nop 0
	v_lshl_add_u32 v2, v1, 13, 16
	v_add3_u32 v2, v2, v11, v176
	ds_read_b128 v[2:5], v2 offset:12288
	v_lshl_add_u64 v[6:7], v[6:7], 0, v[32:33]
	v_lshl_add_u64 v[6:7], v[6:7], 0, v[176:177]
	v_ashrrev_i32_e32 v1, 9, v18
	v_bfe_u32 v8, v18, 5, 4
	s_waitcnt lgkmcnt(0)
	global_store_dwordx4 v[6:7], v[2:5], off
	v_mad_i64_i32 v[6:7], s[12:13], v1, s40, v[28:29]
	s_nop 0
	v_lshl_add_u32 v2, v1, 13, 16
	v_lshlrev_b32_e32 v3, 9, v8
	v_add3_u32 v2, v2, v3, v176
	ds_read_b128 v[2:5], v2 offset:12288
	v_or_b32_e32 v8, s20, v8
	v_ashrrev_i32_e32 v9, 31, v8
	v_lshlrev_b64 v[8:9], 9, v[8:9]
	v_lshl_add_u64 v[6:7], v[6:7], 0, v[8:9]
	v_lshl_add_u64 v[6:7], v[6:7], 0, v[176:177]
	v_ashrrev_i32_e32 v1, 9, v20
	s_waitcnt lgkmcnt(0)
	global_store_dwordx4 v[6:7], v[2:5], off
	v_mad_i64_i32 v[6:7], s[12:13], v1, s40, v[28:29]
	s_nop 0
	v_lshl_add_u32 v2, v1, 13, 16
	v_add3_u32 v2, v2, v11, v176
	ds_read_b128 v[2:5], v2 offset:12288
	v_lshl_add_u64 v[6:7], v[6:7], 0, v[32:33]
	v_lshl_add_u64 v[6:7], v[6:7], 0, v[176:177]
	v_ashrrev_i32_e32 v1, 9, v22
	v_bfe_u32 v8, v22, 5, 4
	s_waitcnt lgkmcnt(0)
	global_store_dwordx4 v[6:7], v[2:5], off
	v_mad_i64_i32 v[6:7], s[12:13], v1, s40, v[28:29]
	s_nop 0
	v_lshl_add_u32 v2, v1, 13, 16
	v_lshlrev_b32_e32 v3, 9, v8
	v_add3_u32 v2, v2, v3, v176
	ds_read_b128 v[2:5], v2 offset:12288
	v_or_b32_e32 v8, s20, v8
	v_ashrrev_i32_e32 v9, 31, v8
	v_lshlrev_b64 v[8:9], 9, v[8:9]
	v_lshl_add_u64 v[6:7], v[6:7], 0, v[8:9]
	v_add_u32_e32 v1, 0xc00, v0
	v_lshl_add_u64 v[6:7], v[6:7], 0, v[176:177]
	v_ashrrev_i32_e32 v1, 9, v1
	s_waitcnt lgkmcnt(0)
	global_store_dwordx4 v[6:7], v[2:5], off
	v_mad_i64_i32 v[6:7], s[12:13], v1, s40, v[28:29]
	s_nop 0
	v_lshl_add_u32 v2, v1, 13, 16
	v_add3_u32 v2, v2, v11, v176
	ds_read_b128 v[2:5], v2 offset:12288
	v_lshl_add_u64 v[6:7], v[6:7], 0, v[32:33]
	v_lshl_add_u64 v[6:7], v[6:7], 0, v[176:177]
	v_add_u32_e32 v0, 0xd00, v0
	s_waitcnt lgkmcnt(0)
	global_store_dwordx4 v[6:7], v[2:5], off
	v_bfe_u32 v6, v0, 5, 4
	s_nop 0
	v_ashrrev_i32_e32 v4, 9, v0
	v_lshl_add_u32 v0, v4, 13, 16
	v_lshlrev_b32_e32 v1, 9, v6
	v_add3_u32 v0, v0, v1, v176
	ds_read_b128 v[0:3], v0 offset:12288
	v_or_b32_e32 v6, s20, v6
	v_ashrrev_i32_e32 v7, 31, v6
	v_mad_i64_i32 v[4:5], s[12:13], v4, s40, v[28:29]
	v_lshlrev_b64 v[6:7], 9, v[6:7]
	v_lshl_add_u64 v[4:5], v[4:5], 0, v[6:7]
	v_lshl_add_u64 v[4:5], v[4:5], 0, v[176:177]
	s_waitcnt lgkmcnt(0)
	global_store_dwordx4 v[4:5], v[0:3], off
	s_barrier
	s_cbranch_scc0 .LBB0_177

.LBB0_534:
	s_or_b64 exec, exec, s[18:19]
	s_and_b32 s18, s37, 1
	s_mul_i32 s19, s18, 0x6000
	s_add_i32 s19, s19, 16
	v_lshl_add_u32 v128, v123, 2, s19
	v_lshl_add_u32 v129, v119, 2, s19
	s_lshl_b32 s18, s18, 10
	v_add_u32_e32 v127, s18, v124
	ds_read_b128 v[20:23], v128 offset:256
	ds_read_b128 v[24:27], v128 offset:272
	ds_read_b128 v[44:47], v128 offset:768
	ds_read_b128 v[48:51], v128 offset:784
	ds_read_b32 v64, v129 offset:1280
	ds_read_b128 v[28:31], v128 offset:512
	ds_read_b128 v[40:43], v128 offset:528
	ds_read_b128 v[12:15], v128 offset:0
	ds_read_b128 v[16:19], v128 offset:16
	s_waitcnt lgkmcnt(7)
	v_pk_mul_f32 v[66:67], v[34:35], v[22:23]
	s_nop 0
	v_pk_fma_f32 v[66:67], v[32:33], v[20:21], v[66:67]
	s_nop 0
	v_pk_fma_f32 v[66:67], v[36:37], v[24:25], v[66:67]
	s_nop 0
	v_pk_fma_f32 v[66:67], v[38:39], v[26:27], v[66:67]
	ds_read_b128 v[20:23], v128 offset:1792
	ds_read_b128 v[24:27], v128 offset:1808
	ds_read_b128 v[56:59], v128 offset:1024
	ds_read_b128 v[60:63], v128 offset:1040
	v_add_f32_e32 v66, v66, v67
	s_nop 1
	v_add_f32_dpp v66, v66, v66 quad_perm:[1,0,3,2] row_mask:0xf bank_mask:0xf bound_ctrl:1
	s_nop 1
	v_add_f32_dpp v66, v66, v66 quad_perm:[2,3,0,1] row_mask:0xf bank_mask:0xf bound_ctrl:1
	s_nop 1
	v_add_f32_dpp v66, v66, v66 row_half_mirror row_mask:0xf bank_mask:0xf bound_ctrl:1
	s_waitcnt lgkmcnt(4)
	v_pk_mul_f32 v[70:71], v[28:29], v[66:67] op_sel_hi:[1,0]
	v_pk_mul_f32 v[72:73], v[30:31], v[66:67] op_sel_hi:[1,0]
	v_pk_mul_f32 v[74:75], v[40:41], v[66:67] op_sel_hi:[1,0]
	v_pk_mul_f32 v[76:77], v[42:43], v[66:67] op_sel_hi:[1,0]
	v_pk_fma_f32 v[70:71], v[44:45], v[64:65], v[70:71] op_sel_hi:[1,0,1]
	v_pk_fma_f32 v[72:73], v[46:47], v[64:65], v[72:73] op_sel_hi:[1,0,1]
	v_pk_fma_f32 v[74:75], v[48:49], v[64:65], v[74:75] op_sel_hi:[1,0,1]
	v_pk_fma_f32 v[76:77], v[50:51], v[64:65], v[76:77] op_sel_hi:[1,0,1]
	v_pk_fma_f32 v[32:33], v[32:33], v[12:13], v[70:71]
	v_pk_fma_f32 v[34:35], v[34:35], v[14:15], v[72:73]
	v_pk_fma_f32 v[36:37], v[36:37], v[16:17], v[74:75]
	v_pk_fma_f32 v[38:39], v[38:39], v[18:19], v[76:77]
	ds_read_b128 v[44:47], v128 offset:2304
	ds_read_b128 v[48:51], v128 offset:2320
	ds_read_b32 v64, v129 offset:2816
	ds_read_b128 v[28:31], v128 offset:2048
	ds_read_b128 v[40:43], v128 offset:2064
	ds_read_b128 v[12:15], v128 offset:1536
	ds_read_b128 v[16:19], v128 offset:1552
	s_waitcnt lgkmcnt(7)
	v_pk_mul_f32 v[66:67], v[34:35], v[22:23]
	v_pk_mul_f32 v[68:69], v[34:35], v[58:59]
	v_pk_fma_f32 v[66:67], v[32:33], v[20:21], v[66:67]
	v_pk_fma_f32 v[68:69], v[32:33], v[56:57], v[68:69]
	v_pk_fma_f32 v[66:67], v[36:37], v[24:25], v[66:67]
	v_pk_fma_f32 v[68:69], v[36:37], v[60:61], v[68:69]
	v_pk_fma_f32 v[66:67], v[38:39], v[26:27], v[66:67]
	v_pk_fma_f32 v[68:69], v[38:39], v[62:63], v[68:69]
	v_add_f32_e32 v66, v66, v67
	v_add_f32_e32 v68, v68, v69
	ds_read_b128 v[20:23], v128 offset:3328
	v_add_f32_dpp v66, v66, v66 quad_perm:[1,0,3,2] row_mask:0xf bank_mask:0xf bound_ctrl:1
	v_add_f32_dpp v68, v68, v68 quad_perm:[1,0,3,2] row_mask:0xf bank_mask:0xf bound_ctrl:1
	ds_read_b128 v[24:27], v128 offset:3344
	v_add_f32_dpp v66, v66, v66 quad_perm:[2,3,0,1] row_mask:0xf bank_mask:0xf bound_ctrl:1
	v_add_f32_dpp v68, v68, v68 quad_perm:[2,3,0,1] row_mask:0xf bank_mask:0xf bound_ctrl:1
	ds_read_b128 v[56:59], v128 offset:2560
	v_add_f32_dpp v66, v66, v66 row_half_mirror row_mask:0xf bank_mask:0xf bound_ctrl:1
	v_add_f32_dpp v68, v68, v68 row_half_mirror row_mask:0xf bank_mask:0xf bound_ctrl:1
	ds_read_b128 v[60:63], v128 offset:2576
	s_waitcnt lgkmcnt(4)
	v_pk_mul_f32 v[70:71], v[28:29], v[66:67] op_sel_hi:[1,0]
	v_pk_mul_f32 v[72:73], v[30:31], v[66:67] op_sel_hi:[1,0]
	v_mov_b32_dpp v69, v68 row_ror:8 row_mask:0xf bank_mask:0xf bound_ctrl:1
	v_pk_mul_f32 v[74:75], v[40:41], v[66:67] op_sel_hi:[1,0]
	v_pk_mul_f32 v[76:77], v[42:43], v[66:67] op_sel_hi:[1,0]
	v_pk_fma_f32 v[70:71], v[44:45], v[64:65], v[70:71] op_sel_hi:[1,0,1]
	v_pk_fma_f32 v[72:73], v[46:47], v[64:65], v[72:73] op_sel_hi:[1,0,1]
	v_pk_fma_f32 v[74:75], v[48:49], v[64:65], v[74:75] op_sel_hi:[1,0,1]
	v_pk_fma_f32 v[76:77], v[50:51], v[64:65], v[76:77] op_sel_hi:[1,0,1]
	v_pk_fma_f32 v[32:33], v[32:33], v[12:13], v[70:71]
	v_pk_fma_f32 v[34:35], v[34:35], v[14:15], v[72:73]
	v_pk_fma_f32 v[36:37], v[36:37], v[16:17], v[74:75]
	v_pk_fma_f32 v[38:39], v[38:39], v[18:19], v[76:77]
	s_and_saveexec_b64 s[18:19], s[12:13]
	v_cvt_pk_bf16_f32 v68, v68, v69
	ds_write_b32 v127, v68 offset:49152
	s_or_b64 exec, exec, s[18:19]
	ds_read_b128 v[44:47], v128 offset:3840
	ds_read_b128 v[48:51], v128 offset:3856
	ds_read_b32 v64, v129 offset:4352
	ds_read_b128 v[28:31], v128 offset:3584
	ds_read_b128 v[40:43], v128 offset:3600
	ds_read_b128 v[12:15], v128 offset:3072
	ds_read_b128 v[16:19], v128 offset:3088
	s_waitcnt lgkmcnt(8)
	v_pk_mul_f32 v[66:67], v[34:35], v[22:23]
	v_pk_mul_f32 v[68:69], v[34:35], v[58:59]
	v_pk_fma_f32 v[66:67], v[32:33], v[20:21], v[66:67]
	v_pk_fma_f32 v[68:69], v[32:33], v[56:57], v[68:69]
	v_pk_fma_f32 v[66:67], v[36:37], v[24:25], v[66:67]
	v_pk_fma_f32 v[68:69], v[36:37], v[60:61], v[68:69]
	v_pk_fma_f32 v[66:67], v[38:39], v[26:27], v[66:67]
	v_pk_fma_f32 v[68:69], v[38:39], v[62:63], v[68:69]
	v_add_f32_e32 v66, v66, v67
	v_add_f32_e32 v68, v68, v69
	ds_read_b128 v[20:23], v128 offset:4864
	v_add_f32_dpp v66, v66, v66 quad_perm:[1,0,3,2] row_mask:0xf bank_mask:0xf bound_ctrl:1
	v_add_f32_dpp v68, v68, v68 quad_perm:[1,0,3,2] row_mask:0xf bank_mask:0xf bound_ctrl:1
	ds_read_b128 v[24:27], v128 offset:4880
	v_add_f32_dpp v66, v66, v66 quad_perm:[2,3,0,1] row_mask:0xf bank_mask:0xf bound_ctrl:1
	v_add_f32_dpp v68, v68, v68 quad_perm:[2,3,0,1] row_mask:0xf bank_mask:0xf bound_ctrl:1
	ds_read_b128 v[56:59], v128 offset:4096
	v_add_f32_dpp v66, v66, v66 row_half_mirror row_mask:0xf bank_mask:0xf bound_ctrl:1
	v_add_f32_dpp v68, v68, v68 row_half_mirror row_mask:0xf bank_mask:0xf bound_ctrl:1
	ds_read_b128 v[60:63], v128 offset:4112
	s_waitcnt lgkmcnt(4)
	v_pk_mul_f32 v[70:71], v[28:29], v[66:67] op_sel_hi:[1,0]
	v_pk_mul_f32 v[72:73], v[30:31], v[66:67] op_sel_hi:[1,0]
	v_mov_b32_dpp v69, v68 row_ror:8 row_mask:0xf bank_mask:0xf bound_ctrl:1
	v_pk_mul_f32 v[74:75], v[40:41], v[66:67] op_sel_hi:[1,0]
	v_pk_mul_f32 v[76:77], v[42:43], v[66:67] op_sel_hi:[1,0]
	v_pk_fma_f32 v[70:71], v[44:45], v[64:65], v[70:71] op_sel_hi:[1,0,1]
	v_pk_fma_f32 v[72:73], v[46:47], v[64:65], v[72:73] op_sel_hi:[1,0,1]
	v_pk_fma_f32 v[74:75], v[48:49], v[64:65], v[74:75] op_sel_hi:[1,0,1]
	v_pk_fma_f32 v[76:77], v[50:51], v[64:65], v[76:77] op_sel_hi:[1,0,1]
	v_pk_fma_f32 v[32:33], v[32:33], v[12:13], v[70:71]
	v_pk_fma_f32 v[34:35], v[34:35], v[14:15], v[72:73]
	v_pk_fma_f32 v[36:37], v[36:37], v[16:17], v[74:75]
	v_pk_fma_f32 v[38:39], v[38:39], v[18:19], v[76:77]
	s_and_saveexec_b64 s[18:19], s[12:13]
	v_cvt_pk_bf16_f32 v68, v68, v69
	ds_write_b32 v127, v68 offset:49216
	s_or_b64 exec, exec, s[18:19]
	ds_read_b128 v[44:47], v128 offset:5376
	ds_read_b128 v[48:51], v128 offset:5392
	ds_read_b32 v64, v129 offset:5888
	ds_read_b128 v[28:31], v128 offset:5120
	ds_read_b128 v[40:43], v128 offset:5136
	ds_read_b128 v[12:15], v128 offset:4608
	ds_read_b128 v[16:19], v128 offset:4624
	s_waitcnt lgkmcnt(8)
	v_pk_mul_f32 v[66:67], v[34:35], v[22:23]
	v_pk_mul_f32 v[68:69], v[34:35], v[58:59]
	v_pk_fma_f32 v[66:67], v[32:33], v[20:21], v[66:67]
	v_pk_fma_f32 v[68:69], v[32:33], v[56:57], v[68:69]
	v_pk_fma_f32 v[66:67], v[36:37], v[24:25], v[66:67]
	v_pk_fma_f32 v[68:69], v[36:37], v[60:61], v[68:69]
	v_pk_fma_f32 v[66:67], v[38:39], v[26:27], v[66:67]
	v_pk_fma_f32 v[68:69], v[38:39], v[62:63], v[68:69]
	v_add_f32_e32 v66, v66, v67
	v_add_f32_e32 v68, v68, v69
	ds_read_b128 v[20:23], v128 offset:6400
	v_add_f32_dpp v66, v66, v66 quad_perm:[1,0,3,2] row_mask:0xf bank_mask:0xf bound_ctrl:1
	v_add_f32_dpp v68, v68, v68 quad_perm:[1,0,3,2] row_mask:0xf bank_mask:0xf bound_ctrl:1
	ds_read_b128 v[24:27], v128 offset:6416
	v_add_f32_dpp v66, v66, v66 quad_perm:[2,3,0,1] row_mask:0xf bank_mask:0xf bound_ctrl:1
	v_add_f32_dpp v68, v68, v68 quad_perm:[2,3,0,1] row_mask:0xf bank_mask:0xf bound_ctrl:1
	ds_read_b128 v[56:59], v128 offset:5632
	v_add_f32_dpp v66, v66, v66 row_half_mirror row_mask:0xf bank_mask:0xf bound_ctrl:1
	v_add_f32_dpp v68, v68, v68 row_half_mirror row_mask:0xf bank_mask:0xf bound_ctrl:1
	ds_read_b128 v[60:63], v128 offset:5648
	s_waitcnt lgkmcnt(4)
	v_pk_mul_f32 v[70:71], v[28:29], v[66:67] op_sel_hi:[1,0]
	v_pk_mul_f32 v[72:73], v[30:31], v[66:67] op_sel_hi:[1,0]
	v_mov_b32_dpp v69, v68 row_ror:8 row_mask:0xf bank_mask:0xf bound_ctrl:1
	v_pk_mul_f32 v[74:75], v[40:41], v[66:67] op_sel_hi:[1,0]
	v_pk_mul_f32 v[76:77], v[42:43], v[66:67] op_sel_hi:[1,0]
	v_pk_fma_f32 v[70:71], v[44:45], v[64:65], v[70:71] op_sel_hi:[1,0,1]
	v_pk_fma_f32 v[72:73], v[46:47], v[64:65], v[72:73] op_sel_hi:[1,0,1]
	v_pk_fma_f32 v[74:75], v[48:49], v[64:65], v[74:75] op_sel_hi:[1,0,1]
	v_pk_fma_f32 v[76:77], v[50:51], v[64:65], v[76:77] op_sel_hi:[1,0,1]
	v_pk_fma_f32 v[32:33], v[32:33], v[12:13], v[70:71]
	v_pk_fma_f32 v[34:35], v[34:35], v[14:15], v[72:73]
	v_pk_fma_f32 v[36:37], v[36:37], v[16:17], v[74:75]
	v_pk_fma_f32 v[38:39], v[38:39], v[18:19], v[76:77]
	s_and_saveexec_b64 s[18:19], s[12:13]
	v_cvt_pk_bf16_f32 v68, v68, v69
	ds_write_b32 v127, v68 offset:49280
	s_or_b64 exec, exec, s[18:19]
	ds_read_b128 v[44:47], v128 offset:6912
	ds_read_b128 v[48:51], v128 offset:6928
	ds_read_b32 v64, v129 offset:7424
	ds_read_b128 v[28:31], v128 offset:6656
	ds_read_b128 v[40:43], v128 offset:6672
	ds_read_b128 v[12:15], v128 offset:6144
	ds_read_b128 v[16:19], v128 offset:6160
	s_waitcnt lgkmcnt(8)
	v_pk_mul_f32 v[66:67], v[34:35], v[22:23]
	v_pk_mul_f32 v[68:69], v[34:35], v[58:59]
	v_pk_fma_f32 v[66:67], v[32:33], v[20:21], v[66:67]
	v_pk_fma_f32 v[68:69], v[32:33], v[56:57], v[68:69]
	v_pk_fma_f32 v[66:67], v[36:37], v[24:25], v[66:67]
	v_pk_fma_f32 v[68:69], v[36:37], v[60:61], v[68:69]
	v_pk_fma_f32 v[66:67], v[38:39], v[26:27], v[66:67]
	v_pk_fma_f32 v[68:69], v[38:39], v[62:63], v[68:69]
	v_add_f32_e32 v66, v66, v67
	v_add_f32_e32 v68, v68, v69
	ds_read_b128 v[20:23], v128 offset:7936
	v_add_f32_dpp v66, v66, v66 quad_perm:[1,0,3,2] row_mask:0xf bank_mask:0xf bound_ctrl:1
	v_add_f32_dpp v68, v68, v68 quad_perm:[1,0,3,2] row_mask:0xf bank_mask:0xf bound_ctrl:1
	ds_read_b128 v[24:27], v128 offset:7952
	v_add_f32_dpp v66, v66, v66 quad_perm:[2,3,0,1] row_mask:0xf bank_mask:0xf bound_ctrl:1
	v_add_f32_dpp v68, v68, v68 quad_perm:[2,3,0,1] row_mask:0xf bank_mask:0xf bound_ctrl:1
	ds_read_b128 v[56:59], v128 offset:7168
	v_add_f32_dpp v66, v66, v66 row_half_mirror row_mask:0xf bank_mask:0xf bound_ctrl:1
	v_add_f32_dpp v68, v68, v68 row_half_mirror row_mask:0xf bank_mask:0xf bound_ctrl:1
	ds_read_b128 v[60:63], v128 offset:7184
	s_waitcnt lgkmcnt(4)
	v_pk_mul_f32 v[70:71], v[28:29], v[66:67] op_sel_hi:[1,0]
	v_pk_mul_f32 v[72:73], v[30:31], v[66:67] op_sel_hi:[1,0]
	v_mov_b32_dpp v69, v68 row_ror:8 row_mask:0xf bank_mask:0xf bound_ctrl:1
	v_pk_mul_f32 v[74:75], v[40:41], v[66:67] op_sel_hi:[1,0]
	v_pk_mul_f32 v[76:77], v[42:43], v[66:67] op_sel_hi:[1,0]
	v_pk_fma_f32 v[70:71], v[44:45], v[64:65], v[70:71] op_sel_hi:[1,0,1]
	v_pk_fma_f32 v[72:73], v[46:47], v[64:65], v[72:73] op_sel_hi:[1,0,1]
	v_pk_fma_f32 v[74:75], v[48:49], v[64:65], v[74:75] op_sel_hi:[1,0,1]
	v_pk_fma_f32 v[76:77], v[50:51], v[64:65], v[76:77] op_sel_hi:[1,0,1]
	v_pk_fma_f32 v[32:33], v[32:33], v[12:13], v[70:71]
	v_pk_fma_f32 v[34:35], v[34:35], v[14:15], v[72:73]
	v_pk_fma_f32 v[36:37], v[36:37], v[16:17], v[74:75]
	v_pk_fma_f32 v[38:39], v[38:39], v[18:19], v[76:77]
	s_and_saveexec_b64 s[18:19], s[12:13]
	v_cvt_pk_bf16_f32 v68, v68, v69
	ds_write_b32 v127, v68 offset:49344
	s_or_b64 exec, exec, s[18:19]
	ds_read_b128 v[44:47], v128 offset:8448
	ds_read_b128 v[48:51], v128 offset:8464
	ds_read_b32 v64, v129 offset:8960
	ds_read_b128 v[28:31], v128 offset:8192
	ds_read_b128 v[40:43], v128 offset:8208
	ds_read_b128 v[12:15], v128 offset:7680
	ds_read_b128 v[16:19], v128 offset:7696
	s_waitcnt lgkmcnt(8)
	v_pk_mul_f32 v[66:67], v[34:35], v[22:23]
	v_pk_mul_f32 v[68:69], v[34:35], v[58:59]
	v_pk_fma_f32 v[66:67], v[32:33], v[20:21], v[66:67]
	v_pk_fma_f32 v[68:69], v[32:33], v[56:57], v[68:69]
	v_pk_fma_f32 v[66:67], v[36:37], v[24:25], v[66:67]
	v_pk_fma_f32 v[68:69], v[36:37], v[60:61], v[68:69]
	v_pk_fma_f32 v[66:67], v[38:39], v[26:27], v[66:67]
	v_pk_fma_f32 v[68:69], v[38:39], v[62:63], v[68:69]
	v_add_f32_e32 v66, v66, v67
	v_add_f32_e32 v68, v68, v69
	ds_read_b128 v[20:23], v128 offset:9472
	v_add_f32_dpp v66, v66, v66 quad_perm:[1,0,3,2] row_mask:0xf bank_mask:0xf bound_ctrl:1
	v_add_f32_dpp v68, v68, v68 quad_perm:[1,0,3,2] row_mask:0xf bank_mask:0xf bound_ctrl:1
	ds_read_b128 v[24:27], v128 offset:9488
	v_add_f32_dpp v66, v66, v66 quad_perm:[2,3,0,1] row_mask:0xf bank_mask:0xf bound_ctrl:1
	v_add_f32_dpp v68, v68, v68 quad_perm:[2,3,0,1] row_mask:0xf bank_mask:0xf bound_ctrl:1
	ds_read_b128 v[56:59], v128 offset:8704
	v_add_f32_dpp v66, v66, v66 row_half_mirror row_mask:0xf bank_mask:0xf bound_ctrl:1
	v_add_f32_dpp v68, v68, v68 row_half_mirror row_mask:0xf bank_mask:0xf bound_ctrl:1
	ds_read_b128 v[60:63], v128 offset:8720
	s_waitcnt lgkmcnt(4)
	v_pk_mul_f32 v[70:71], v[28:29], v[66:67] op_sel_hi:[1,0]
	v_pk_mul_f32 v[72:73], v[30:31], v[66:67] op_sel_hi:[1,0]
	v_mov_b32_dpp v69, v68 row_ror:8 row_mask:0xf bank_mask:0xf bound_ctrl:1
	v_pk_mul_f32 v[74:75], v[40:41], v[66:67] op_sel_hi:[1,0]
	v_pk_mul_f32 v[76:77], v[42:43], v[66:67] op_sel_hi:[1,0]
	v_pk_fma_f32 v[70:71], v[44:45], v[64:65], v[70:71] op_sel_hi:[1,0,1]
	v_pk_fma_f32 v[72:73], v[46:47], v[64:65], v[72:73] op_sel_hi:[1,0,1]
	v_pk_fma_f32 v[74:75], v[48:49], v[64:65], v[74:75] op_sel_hi:[1,0,1]
	v_pk_fma_f32 v[76:77], v[50:51], v[64:65], v[76:77] op_sel_hi:[1,0,1]
	v_pk_fma_f32 v[32:33], v[32:33], v[12:13], v[70:71]
	v_pk_fma_f32 v[34:35], v[34:35], v[14:15], v[72:73]
	v_pk_fma_f32 v[36:37], v[36:37], v[16:17], v[74:75]
	v_pk_fma_f32 v[38:39], v[38:39], v[18:19], v[76:77]
	s_and_saveexec_b64 s[18:19], s[12:13]
	v_cvt_pk_bf16_f32 v68, v68, v69
	ds_write_b32 v127, v68 offset:49408
	s_or_b64 exec, exec, s[18:19]
	ds_read_b128 v[44:47], v128 offset:9984
	ds_read_b128 v[48:51], v128 offset:10000
	ds_read_b32 v64, v129 offset:10496
	ds_read_b128 v[28:31], v128 offset:9728
	ds_read_b128 v[40:43], v128 offset:9744
	ds_read_b128 v[12:15], v128 offset:9216
	ds_read_b128 v[16:19], v128 offset:9232
	s_waitcnt lgkmcnt(8)
	v_pk_mul_f32 v[66:67], v[34:35], v[22:23]
	v_pk_mul_f32 v[68:69], v[34:35], v[58:59]
	v_pk_fma_f32 v[66:67], v[32:33], v[20:21], v[66:67]
	v_pk_fma_f32 v[68:69], v[32:33], v[56:57], v[68:69]
	v_pk_fma_f32 v[66:67], v[36:37], v[24:25], v[66:67]
	v_pk_fma_f32 v[68:69], v[36:37], v[60:61], v[68:69]
	v_pk_fma_f32 v[66:67], v[38:39], v[26:27], v[66:67]
	v_pk_fma_f32 v[68:69], v[38:39], v[62:63], v[68:69]
	v_add_f32_e32 v66, v66, v67
	v_add_f32_e32 v68, v68, v69
	ds_read_b128 v[20:23], v128 offset:11008
	v_add_f32_dpp v66, v66, v66 quad_perm:[1,0,3,2] row_mask:0xf bank_mask:0xf bound_ctrl:1
	v_add_f32_dpp v68, v68, v68 quad_perm:[1,0,3,2] row_mask:0xf bank_mask:0xf bound_ctrl:1
	ds_read_b128 v[24:27], v128 offset:11024
	v_add_f32_dpp v66, v66, v66 quad_perm:[2,3,0,1] row_mask:0xf bank_mask:0xf bound_ctrl:1
	v_add_f32_dpp v68, v68, v68 quad_perm:[2,3,0,1] row_mask:0xf bank_mask:0xf bound_ctrl:1
	ds_read_b128 v[56:59], v128 offset:10240
	v_add_f32_dpp v66, v66, v66 row_half_mirror row_mask:0xf bank_mask:0xf bound_ctrl:1
	v_add_f32_dpp v68, v68, v68 row_half_mirror row_mask:0xf bank_mask:0xf bound_ctrl:1
	ds_read_b128 v[60:63], v128 offset:10256
	s_waitcnt lgkmcnt(4)
	v_pk_mul_f32 v[70:71], v[28:29], v[66:67] op_sel_hi:[1,0]
	v_pk_mul_f32 v[72:73], v[30:31], v[66:67] op_sel_hi:[1,0]
	v_mov_b32_dpp v69, v68 row_ror:8 row_mask:0xf bank_mask:0xf bound_ctrl:1
	v_pk_mul_f32 v[74:75], v[40:41], v[66:67] op_sel_hi:[1,0]
	v_pk_mul_f32 v[76:77], v[42:43], v[66:67] op_sel_hi:[1,0]
	v_pk_fma_f32 v[70:71], v[44:45], v[64:65], v[70:71] op_sel_hi:[1,0,1]
	v_pk_fma_f32 v[72:73], v[46:47], v[64:65], v[72:73] op_sel_hi:[1,0,1]
	v_pk_fma_f32 v[74:75], v[48:49], v[64:65], v[74:75] op_sel_hi:[1,0,1]
	v_pk_fma_f32 v[76:77], v[50:51], v[64:65], v[76:77] op_sel_hi:[1,0,1]
	v_pk_fma_f32 v[32:33], v[32:33], v[12:13], v[70:71]
	v_pk_fma_f32 v[34:35], v[34:35], v[14:15], v[72:73]
	v_pk_fma_f32 v[36:37], v[36:37], v[16:17], v[74:75]
	v_pk_fma_f32 v[38:39], v[38:39], v[18:19], v[76:77]
	s_and_saveexec_b64 s[18:19], s[12:13]
	v_cvt_pk_bf16_f32 v68, v68, v69
	ds_write_b32 v127, v68 offset:49472
	s_or_b64 exec, exec, s[18:19]
	ds_read_b128 v[44:47], v128 offset:11520
	ds_read_b128 v[48:51], v128 offset:11536
	ds_read_b32 v64, v129 offset:12032
	ds_read_b128 v[28:31], v128 offset:11264
	ds_read_b128 v[40:43], v128 offset:11280
	ds_read_b128 v[12:15], v128 offset:10752
	ds_read_b128 v[16:19], v128 offset:10768
	s_waitcnt lgkmcnt(8)
	v_pk_mul_f32 v[66:67], v[34:35], v[22:23]
	v_pk_mul_f32 v[68:69], v[34:35], v[58:59]
	v_pk_fma_f32 v[66:67], v[32:33], v[20:21], v[66:67]
	v_pk_fma_f32 v[68:69], v[32:33], v[56:57], v[68:69]
	v_pk_fma_f32 v[66:67], v[36:37], v[24:25], v[66:67]
	v_pk_fma_f32 v[68:69], v[36:37], v[60:61], v[68:69]
	v_pk_fma_f32 v[66:67], v[38:39], v[26:27], v[66:67]
	v_pk_fma_f32 v[68:69], v[38:39], v[62:63], v[68:69]
	v_add_f32_e32 v66, v66, v67
	v_add_f32_e32 v68, v68, v69
	ds_read_b128 v[20:23], v128 offset:12544
	v_add_f32_dpp v66, v66, v66 quad_perm:[1,0,3,2] row_mask:0xf bank_mask:0xf bound_ctrl:1
	v_add_f32_dpp v68, v68, v68 quad_perm:[1,0,3,2] row_mask:0xf bank_mask:0xf bound_ctrl:1
	ds_read_b128 v[24:27], v128 offset:12560
	v_add_f32_dpp v66, v66, v66 quad_perm:[2,3,0,1] row_mask:0xf bank_mask:0xf bound_ctrl:1
	v_add_f32_dpp v68, v68, v68 quad_perm:[2,3,0,1] row_mask:0xf bank_mask:0xf bound_ctrl:1
	ds_read_b128 v[56:59], v128 offset:11776
	v_add_f32_dpp v66, v66, v66 row_half_mirror row_mask:0xf bank_mask:0xf bound_ctrl:1
	v_add_f32_dpp v68, v68, v68 row_half_mirror row_mask:0xf bank_mask:0xf bound_ctrl:1
	ds_read_b128 v[60:63], v128 offset:11792
	s_waitcnt lgkmcnt(4)
	v_pk_mul_f32 v[70:71], v[28:29], v[66:67] op_sel_hi:[1,0]
	v_pk_mul_f32 v[72:73], v[30:31], v[66:67] op_sel_hi:[1,0]
	v_mov_b32_dpp v69, v68 row_ror:8 row_mask:0xf bank_mask:0xf bound_ctrl:1
	v_pk_mul_f32 v[74:75], v[40:41], v[66:67] op_sel_hi:[1,0]
	v_pk_mul_f32 v[76:77], v[42:43], v[66:67] op_sel_hi:[1,0]
	v_pk_fma_f32 v[70:71], v[44:45], v[64:65], v[70:71] op_sel_hi:[1,0,1]
	v_pk_fma_f32 v[72:73], v[46:47], v[64:65], v[72:73] op_sel_hi:[1,0,1]
	v_pk_fma_f32 v[74:75], v[48:49], v[64:65], v[74:75] op_sel_hi:[1,0,1]
	v_pk_fma_f32 v[76:77], v[50:51], v[64:65], v[76:77] op_sel_hi:[1,0,1]
	v_pk_fma_f32 v[32:33], v[32:33], v[12:13], v[70:71]
	v_pk_fma_f32 v[34:35], v[34:35], v[14:15], v[72:73]
	v_pk_fma_f32 v[36:37], v[36:37], v[16:17], v[74:75]
	v_pk_fma_f32 v[38:39], v[38:39], v[18:19], v[76:77]
	s_and_saveexec_b64 s[18:19], s[12:13]
	v_cvt_pk_bf16_f32 v68, v68, v69
	ds_write_b32 v127, v68 offset:49536
	s_or_b64 exec, exec, s[18:19]
	ds_read_b128 v[44:47], v128 offset:13056
	ds_read_b128 v[48:51], v128 offset:13072
	ds_read_b32 v64, v129 offset:13568
	ds_read_b128 v[28:31], v128 offset:12800
	ds_read_b128 v[40:43], v128 offset:12816
	ds_read_b128 v[12:15], v128 offset:12288
	ds_read_b128 v[16:19], v128 offset:12304
	s_waitcnt lgkmcnt(8)
	v_pk_mul_f32 v[66:67], v[34:35], v[22:23]
	v_pk_mul_f32 v[68:69], v[34:35], v[58:59]
	v_pk_fma_f32 v[66:67], v[32:33], v[20:21], v[66:67]
	v_pk_fma_f32 v[68:69], v[32:33], v[56:57], v[68:69]
	v_pk_fma_f32 v[66:67], v[36:37], v[24:25], v[66:67]
	v_pk_fma_f32 v[68:69], v[36:37], v[60:61], v[68:69]
	v_pk_fma_f32 v[66:67], v[38:39], v[26:27], v[66:67]
	v_pk_fma_f32 v[68:69], v[38:39], v[62:63], v[68:69]
	v_add_f32_e32 v66, v66, v67
	v_add_f32_e32 v68, v68, v69
	ds_read_b128 v[20:23], v128 offset:14080
	v_add_f32_dpp v66, v66, v66 quad_perm:[1,0,3,2] row_mask:0xf bank_mask:0xf bound_ctrl:1
	v_add_f32_dpp v68, v68, v68 quad_perm:[1,0,3,2] row_mask:0xf bank_mask:0xf bound_ctrl:1
	ds_read_b128 v[24:27], v128 offset:14096
	v_add_f32_dpp v66, v66, v66 quad_perm:[2,3,0,1] row_mask:0xf bank_mask:0xf bound_ctrl:1
	v_add_f32_dpp v68, v68, v68 quad_perm:[2,3,0,1] row_mask:0xf bank_mask:0xf bound_ctrl:1
	ds_read_b128 v[56:59], v128 offset:13312
	v_add_f32_dpp v66, v66, v66 row_half_mirror row_mask:0xf bank_mask:0xf bound_ctrl:1
	v_add_f32_dpp v68, v68, v68 row_half_mirror row_mask:0xf bank_mask:0xf bound_ctrl:1
	ds_read_b128 v[60:63], v128 offset:13328
	s_waitcnt lgkmcnt(4)
	v_pk_mul_f32 v[70:71], v[28:29], v[66:67] op_sel_hi:[1,0]
	v_pk_mul_f32 v[72:73], v[30:31], v[66:67] op_sel_hi:[1,0]
	v_mov_b32_dpp v69, v68 row_ror:8 row_mask:0xf bank_mask:0xf bound_ctrl:1
	v_pk_mul_f32 v[74:75], v[40:41], v[66:67] op_sel_hi:[1,0]
	v_pk_mul_f32 v[76:77], v[42:43], v[66:67] op_sel_hi:[1,0]
	v_pk_fma_f32 v[70:71], v[44:45], v[64:65], v[70:71] op_sel_hi:[1,0,1]
	v_pk_fma_f32 v[72:73], v[46:47], v[64:65], v[72:73] op_sel_hi:[1,0,1]
	v_pk_fma_f32 v[74:75], v[48:49], v[64:65], v[74:75] op_sel_hi:[1,0,1]
	v_pk_fma_f32 v[76:77], v[50:51], v[64:65], v[76:77] op_sel_hi:[1,0,1]
	v_pk_fma_f32 v[32:33], v[32:33], v[12:13], v[70:71]
	v_pk_fma_f32 v[34:35], v[34:35], v[14:15], v[72:73]
	v_pk_fma_f32 v[36:37], v[36:37], v[16:17], v[74:75]
	v_pk_fma_f32 v[38:39], v[38:39], v[18:19], v[76:77]
	s_and_saveexec_b64 s[18:19], s[12:13]
	v_cvt_pk_bf16_f32 v68, v68, v69
	ds_write_b32 v127, v68 offset:49600
	s_or_b64 exec, exec, s[18:19]
	ds_read_b128 v[44:47], v128 offset:14592
	ds_read_b128 v[48:51], v128 offset:14608
	ds_read_b32 v64, v129 offset:15104
	ds_read_b128 v[28:31], v128 offset:14336
	ds_read_b128 v[40:43], v128 offset:14352
	ds_read_b128 v[12:15], v128 offset:13824
	ds_read_b128 v[16:19], v128 offset:13840
	s_waitcnt lgkmcnt(8)
	v_pk_mul_f32 v[66:67], v[34:35], v[22:23]
	v_pk_mul_f32 v[68:69], v[34:35], v[58:59]
	v_pk_fma_f32 v[66:67], v[32:33], v[20:21], v[66:67]
	v_pk_fma_f32 v[68:69], v[32:33], v[56:57], v[68:69]
	v_pk_fma_f32 v[66:67], v[36:37], v[24:25], v[66:67]
	v_pk_fma_f32 v[68:69], v[36:37], v[60:61], v[68:69]
	v_pk_fma_f32 v[66:67], v[38:39], v[26:27], v[66:67]
	v_pk_fma_f32 v[68:69], v[38:39], v[62:63], v[68:69]
	v_add_f32_e32 v66, v66, v67
	v_add_f32_e32 v68, v68, v69
	ds_read_b128 v[20:23], v128 offset:15616
	v_add_f32_dpp v66, v66, v66 quad_perm:[1,0,3,2] row_mask:0xf bank_mask:0xf bound_ctrl:1
	v_add_f32_dpp v68, v68, v68 quad_perm:[1,0,3,2] row_mask:0xf bank_mask:0xf bound_ctrl:1
	ds_read_b128 v[24:27], v128 offset:15632
	v_add_f32_dpp v66, v66, v66 quad_perm:[2,3,0,1] row_mask:0xf bank_mask:0xf bound_ctrl:1
	v_add_f32_dpp v68, v68, v68 quad_perm:[2,3,0,1] row_mask:0xf bank_mask:0xf bound_ctrl:1
	ds_read_b128 v[56:59], v128 offset:14848
	v_add_f32_dpp v66, v66, v66 row_half_mirror row_mask:0xf bank_mask:0xf bound_ctrl:1
	v_add_f32_dpp v68, v68, v68 row_half_mirror row_mask:0xf bank_mask:0xf bound_ctrl:1
	ds_read_b128 v[60:63], v128 offset:14864
	s_waitcnt lgkmcnt(4)
	v_pk_mul_f32 v[70:71], v[28:29], v[66:67] op_sel_hi:[1,0]
	v_pk_mul_f32 v[72:73], v[30:31], v[66:67] op_sel_hi:[1,0]
	v_mov_b32_dpp v69, v68 row_ror:8 row_mask:0xf bank_mask:0xf bound_ctrl:1
	v_pk_mul_f32 v[74:75], v[40:41], v[66:67] op_sel_hi:[1,0]
	v_pk_mul_f32 v[76:77], v[42:43], v[66:67] op_sel_hi:[1,0]
	v_pk_fma_f32 v[70:71], v[44:45], v[64:65], v[70:71] op_sel_hi:[1,0,1]
	v_pk_fma_f32 v[72:73], v[46:47], v[64:65], v[72:73] op_sel_hi:[1,0,1]
	v_pk_fma_f32 v[74:75], v[48:49], v[64:65], v[74:75] op_sel_hi:[1,0,1]
	v_pk_fma_f32 v[76:77], v[50:51], v[64:65], v[76:77] op_sel_hi:[1,0,1]
	v_pk_fma_f32 v[32:33], v[32:33], v[12:13], v[70:71]
	v_pk_fma_f32 v[34:35], v[34:35], v[14:15], v[72:73]
	v_pk_fma_f32 v[36:37], v[36:37], v[16:17], v[74:75]
	v_pk_fma_f32 v[38:39], v[38:39], v[18:19], v[76:77]
	s_and_saveexec_b64 s[18:19], s[12:13]
	v_cvt_pk_bf16_f32 v68, v68, v69
	ds_write_b32 v127, v68 offset:49664
	s_or_b64 exec, exec, s[18:19]
	ds_read_b128 v[44:47], v128 offset:16128
	ds_read_b128 v[48:51], v128 offset:16144
	ds_read_b32 v64, v129 offset:16640
	ds_read_b128 v[28:31], v128 offset:15872
	ds_read_b128 v[40:43], v128 offset:15888
	ds_read_b128 v[12:15], v128 offset:15360
	ds_read_b128 v[16:19], v128 offset:15376
	s_waitcnt lgkmcnt(8)
	v_pk_mul_f32 v[66:67], v[34:35], v[22:23]
	v_pk_mul_f32 v[68:69], v[34:35], v[58:59]
	v_pk_fma_f32 v[66:67], v[32:33], v[20:21], v[66:67]
	v_pk_fma_f32 v[68:69], v[32:33], v[56:57], v[68:69]
	v_pk_fma_f32 v[66:67], v[36:37], v[24:25], v[66:67]
	v_pk_fma_f32 v[68:69], v[36:37], v[60:61], v[68:69]
	v_pk_fma_f32 v[66:67], v[38:39], v[26:27], v[66:67]
	v_pk_fma_f32 v[68:69], v[38:39], v[62:63], v[68:69]
	v_add_f32_e32 v66, v66, v67
	v_add_f32_e32 v68, v68, v69
	ds_read_b128 v[20:23], v128 offset:17152
	v_add_f32_dpp v66, v66, v66 quad_perm:[1,0,3,2] row_mask:0xf bank_mask:0xf bound_ctrl:1
	v_add_f32_dpp v68, v68, v68 quad_perm:[1,0,3,2] row_mask:0xf bank_mask:0xf bound_ctrl:1
	ds_read_b128 v[24:27], v128 offset:17168
	v_add_f32_dpp v66, v66, v66 quad_perm:[2,3,0,1] row_mask:0xf bank_mask:0xf bound_ctrl:1
	v_add_f32_dpp v68, v68, v68 quad_perm:[2,3,0,1] row_mask:0xf bank_mask:0xf bound_ctrl:1
	ds_read_b128 v[56:59], v128 offset:16384
	v_add_f32_dpp v66, v66, v66 row_half_mirror row_mask:0xf bank_mask:0xf bound_ctrl:1
	v_add_f32_dpp v68, v68, v68 row_half_mirror row_mask:0xf bank_mask:0xf bound_ctrl:1
	ds_read_b128 v[60:63], v128 offset:16400
	s_waitcnt lgkmcnt(4)
	v_pk_mul_f32 v[70:71], v[28:29], v[66:67] op_sel_hi:[1,0]
	v_pk_mul_f32 v[72:73], v[30:31], v[66:67] op_sel_hi:[1,0]
	v_mov_b32_dpp v69, v68 row_ror:8 row_mask:0xf bank_mask:0xf bound_ctrl:1
	v_pk_mul_f32 v[74:75], v[40:41], v[66:67] op_sel_hi:[1,0]
	v_pk_mul_f32 v[76:77], v[42:43], v[66:67] op_sel_hi:[1,0]
	v_pk_fma_f32 v[70:71], v[44:45], v[64:65], v[70:71] op_sel_hi:[1,0,1]
	v_pk_fma_f32 v[72:73], v[46:47], v[64:65], v[72:73] op_sel_hi:[1,0,1]
	v_pk_fma_f32 v[74:75], v[48:49], v[64:65], v[74:75] op_sel_hi:[1,0,1]
	v_pk_fma_f32 v[76:77], v[50:51], v[64:65], v[76:77] op_sel_hi:[1,0,1]
	v_pk_fma_f32 v[32:33], v[32:33], v[12:13], v[70:71]
	v_pk_fma_f32 v[34:35], v[34:35], v[14:15], v[72:73]
	v_pk_fma_f32 v[36:37], v[36:37], v[16:17], v[74:75]
	v_pk_fma_f32 v[38:39], v[38:39], v[18:19], v[76:77]
	s_and_saveexec_b64 s[18:19], s[12:13]
	v_cvt_pk_bf16_f32 v68, v68, v69
	ds_write_b32 v127, v68 offset:49728
	s_or_b64 exec, exec, s[18:19]
	ds_read_b128 v[44:47], v128 offset:17664
	ds_read_b128 v[48:51], v128 offset:17680
	ds_read_b32 v64, v129 offset:18176
	ds_read_b128 v[28:31], v128 offset:17408
	ds_read_b128 v[40:43], v128 offset:17424
	ds_read_b128 v[12:15], v128 offset:16896
	ds_read_b128 v[16:19], v128 offset:16912
	s_waitcnt lgkmcnt(8)
	v_pk_mul_f32 v[66:67], v[34:35], v[22:23]
	v_pk_mul_f32 v[68:69], v[34:35], v[58:59]
	v_pk_fma_f32 v[66:67], v[32:33], v[20:21], v[66:67]
	v_pk_fma_f32 v[68:69], v[32:33], v[56:57], v[68:69]
	v_pk_fma_f32 v[66:67], v[36:37], v[24:25], v[66:67]
	v_pk_fma_f32 v[68:69], v[36:37], v[60:61], v[68:69]
	v_pk_fma_f32 v[66:67], v[38:39], v[26:27], v[66:67]
	v_pk_fma_f32 v[68:69], v[38:39], v[62:63], v[68:69]
	v_add_f32_e32 v66, v66, v67
	v_add_f32_e32 v68, v68, v69
	ds_read_b128 v[20:23], v128 offset:18688
	v_add_f32_dpp v66, v66, v66 quad_perm:[1,0,3,2] row_mask:0xf bank_mask:0xf bound_ctrl:1
	v_add_f32_dpp v68, v68, v68 quad_perm:[1,0,3,2] row_mask:0xf bank_mask:0xf bound_ctrl:1
	ds_read_b128 v[24:27], v128 offset:18704
	v_add_f32_dpp v66, v66, v66 quad_perm:[2,3,0,1] row_mask:0xf bank_mask:0xf bound_ctrl:1
	v_add_f32_dpp v68, v68, v68 quad_perm:[2,3,0,1] row_mask:0xf bank_mask:0xf bound_ctrl:1
	ds_read_b128 v[56:59], v128 offset:17920
	v_add_f32_dpp v66, v66, v66 row_half_mirror row_mask:0xf bank_mask:0xf bound_ctrl:1
	v_add_f32_dpp v68, v68, v68 row_half_mirror row_mask:0xf bank_mask:0xf bound_ctrl:1
	ds_read_b128 v[60:63], v128 offset:17936
	s_waitcnt lgkmcnt(4)
	v_pk_mul_f32 v[70:71], v[28:29], v[66:67] op_sel_hi:[1,0]
	v_pk_mul_f32 v[72:73], v[30:31], v[66:67] op_sel_hi:[1,0]
	v_mov_b32_dpp v69, v68 row_ror:8 row_mask:0xf bank_mask:0xf bound_ctrl:1
	v_pk_mul_f32 v[74:75], v[40:41], v[66:67] op_sel_hi:[1,0]
	v_pk_mul_f32 v[76:77], v[42:43], v[66:67] op_sel_hi:[1,0]
	v_pk_fma_f32 v[70:71], v[44:45], v[64:65], v[70:71] op_sel_hi:[1,0,1]
	v_pk_fma_f32 v[72:73], v[46:47], v[64:65], v[72:73] op_sel_hi:[1,0,1]
	v_pk_fma_f32 v[74:75], v[48:49], v[64:65], v[74:75] op_sel_hi:[1,0,1]
	v_pk_fma_f32 v[76:77], v[50:51], v[64:65], v[76:77] op_sel_hi:[1,0,1]
	v_pk_fma_f32 v[32:33], v[32:33], v[12:13], v[70:71]
	v_pk_fma_f32 v[34:35], v[34:35], v[14:15], v[72:73]
	v_pk_fma_f32 v[36:37], v[36:37], v[16:17], v[74:75]
	v_pk_fma_f32 v[38:39], v[38:39], v[18:19], v[76:77]
	s_and_saveexec_b64 s[18:19], s[12:13]
	v_cvt_pk_bf16_f32 v68, v68, v69
	ds_write_b32 v127, v68 offset:49792
	s_or_b64 exec, exec, s[18:19]
	ds_read_b128 v[44:47], v128 offset:19200
	ds_read_b128 v[48:51], v128 offset:19216
	ds_read_b32 v64, v129 offset:19712
	ds_read_b128 v[28:31], v128 offset:18944
	ds_read_b128 v[40:43], v128 offset:18960
	ds_read_b128 v[12:15], v128 offset:18432
	ds_read_b128 v[16:19], v128 offset:18448
	s_waitcnt lgkmcnt(8)
	v_pk_mul_f32 v[66:67], v[34:35], v[22:23]
	v_pk_mul_f32 v[68:69], v[34:35], v[58:59]
	v_pk_fma_f32 v[66:67], v[32:33], v[20:21], v[66:67]
	v_pk_fma_f32 v[68:69], v[32:33], v[56:57], v[68:69]
	v_pk_fma_f32 v[66:67], v[36:37], v[24:25], v[66:67]
	v_pk_fma_f32 v[68:69], v[36:37], v[60:61], v[68:69]
	v_pk_fma_f32 v[66:67], v[38:39], v[26:27], v[66:67]
	v_pk_fma_f32 v[68:69], v[38:39], v[62:63], v[68:69]
	v_add_f32_e32 v66, v66, v67
	v_add_f32_e32 v68, v68, v69
	ds_read_b128 v[20:23], v128 offset:20224
	v_add_f32_dpp v66, v66, v66 quad_perm:[1,0,3,2] row_mask:0xf bank_mask:0xf bound_ctrl:1
	v_add_f32_dpp v68, v68, v68 quad_perm:[1,0,3,2] row_mask:0xf bank_mask:0xf bound_ctrl:1
	ds_read_b128 v[24:27], v128 offset:20240
	v_add_f32_dpp v66, v66, v66 quad_perm:[2,3,0,1] row_mask:0xf bank_mask:0xf bound_ctrl:1
	v_add_f32_dpp v68, v68, v68 quad_perm:[2,3,0,1] row_mask:0xf bank_mask:0xf bound_ctrl:1
	ds_read_b128 v[56:59], v128 offset:19456
	v_add_f32_dpp v66, v66, v66 row_half_mirror row_mask:0xf bank_mask:0xf bound_ctrl:1
	v_add_f32_dpp v68, v68, v68 row_half_mirror row_mask:0xf bank_mask:0xf bound_ctrl:1
	ds_read_b128 v[60:63], v128 offset:19472
	s_waitcnt lgkmcnt(4)
	v_pk_mul_f32 v[70:71], v[28:29], v[66:67] op_sel_hi:[1,0]
	v_pk_mul_f32 v[72:73], v[30:31], v[66:67] op_sel_hi:[1,0]
	v_mov_b32_dpp v69, v68 row_ror:8 row_mask:0xf bank_mask:0xf bound_ctrl:1
	v_pk_mul_f32 v[74:75], v[40:41], v[66:67] op_sel_hi:[1,0]
	v_pk_mul_f32 v[76:77], v[42:43], v[66:67] op_sel_hi:[1,0]
	v_pk_fma_f32 v[70:71], v[44:45], v[64:65], v[70:71] op_sel_hi:[1,0,1]
	v_pk_fma_f32 v[72:73], v[46:47], v[64:65], v[72:73] op_sel_hi:[1,0,1]
	v_pk_fma_f32 v[74:75], v[48:49], v[64:65], v[74:75] op_sel_hi:[1,0,1]
	v_pk_fma_f32 v[76:77], v[50:51], v[64:65], v[76:77] op_sel_hi:[1,0,1]
	v_pk_fma_f32 v[32:33], v[32:33], v[12:13], v[70:71]
	v_pk_fma_f32 v[34:35], v[34:35], v[14:15], v[72:73]
	v_pk_fma_f32 v[36:37], v[36:37], v[16:17], v[74:75]
	v_pk_fma_f32 v[38:39], v[38:39], v[18:19], v[76:77]
	s_and_saveexec_b64 s[18:19], s[12:13]
	v_cvt_pk_bf16_f32 v68, v68, v69
	ds_write_b32 v127, v68 offset:49856
	s_or_b64 exec, exec, s[18:19]
	ds_read_b128 v[44:47], v128 offset:20736
	ds_read_b128 v[48:51], v128 offset:20752
	ds_read_b32 v64, v129 offset:21248
	ds_read_b128 v[28:31], v128 offset:20480
	ds_read_b128 v[40:43], v128 offset:20496
	ds_read_b128 v[12:15], v128 offset:19968
	ds_read_b128 v[16:19], v128 offset:19984
	s_waitcnt lgkmcnt(8)
	v_pk_mul_f32 v[66:67], v[34:35], v[22:23]
	v_pk_mul_f32 v[68:69], v[34:35], v[58:59]
	v_pk_fma_f32 v[66:67], v[32:33], v[20:21], v[66:67]
	v_pk_fma_f32 v[68:69], v[32:33], v[56:57], v[68:69]
	v_pk_fma_f32 v[66:67], v[36:37], v[24:25], v[66:67]
	v_pk_fma_f32 v[68:69], v[36:37], v[60:61], v[68:69]
	v_pk_fma_f32 v[66:67], v[38:39], v[26:27], v[66:67]
	v_pk_fma_f32 v[68:69], v[38:39], v[62:63], v[68:69]
	v_add_f32_e32 v66, v66, v67
	v_add_f32_e32 v68, v68, v69
	ds_read_b128 v[20:23], v128 offset:21760
	v_add_f32_dpp v66, v66, v66 quad_perm:[1,0,3,2] row_mask:0xf bank_mask:0xf bound_ctrl:1
	v_add_f32_dpp v68, v68, v68 quad_perm:[1,0,3,2] row_mask:0xf bank_mask:0xf bound_ctrl:1
	ds_read_b128 v[24:27], v128 offset:21776
	v_add_f32_dpp v66, v66, v66 quad_perm:[2,3,0,1] row_mask:0xf bank_mask:0xf bound_ctrl:1
	v_add_f32_dpp v68, v68, v68 quad_perm:[2,3,0,1] row_mask:0xf bank_mask:0xf bound_ctrl:1
	ds_read_b128 v[56:59], v128 offset:20992
	v_add_f32_dpp v66, v66, v66 row_half_mirror row_mask:0xf bank_mask:0xf bound_ctrl:1
	v_add_f32_dpp v68, v68, v68 row_half_mirror row_mask:0xf bank_mask:0xf bound_ctrl:1
	ds_read_b128 v[60:63], v128 offset:21008
	s_waitcnt lgkmcnt(4)
	v_pk_mul_f32 v[70:71], v[28:29], v[66:67] op_sel_hi:[1,0]
	v_pk_mul_f32 v[72:73], v[30:31], v[66:67] op_sel_hi:[1,0]
	v_mov_b32_dpp v69, v68 row_ror:8 row_mask:0xf bank_mask:0xf bound_ctrl:1
	v_pk_mul_f32 v[74:75], v[40:41], v[66:67] op_sel_hi:[1,0]
	v_pk_mul_f32 v[76:77], v[42:43], v[66:67] op_sel_hi:[1,0]
	v_pk_fma_f32 v[70:71], v[44:45], v[64:65], v[70:71] op_sel_hi:[1,0,1]
	v_pk_fma_f32 v[72:73], v[46:47], v[64:65], v[72:73] op_sel_hi:[1,0,1]
	v_pk_fma_f32 v[74:75], v[48:49], v[64:65], v[74:75] op_sel_hi:[1,0,1]
	v_pk_fma_f32 v[76:77], v[50:51], v[64:65], v[76:77] op_sel_hi:[1,0,1]
	v_pk_fma_f32 v[32:33], v[32:33], v[12:13], v[70:71]
	v_pk_fma_f32 v[34:35], v[34:35], v[14:15], v[72:73]
	v_pk_fma_f32 v[36:37], v[36:37], v[16:17], v[74:75]
	v_pk_fma_f32 v[38:39], v[38:39], v[18:19], v[76:77]
	s_and_saveexec_b64 s[18:19], s[12:13]
	v_cvt_pk_bf16_f32 v68, v68, v69
	ds_write_b32 v127, v68 offset:49920
	s_or_b64 exec, exec, s[18:19]
	ds_read_b128 v[44:47], v128 offset:22272
	ds_read_b128 v[48:51], v128 offset:22288
	ds_read_b32 v64, v129 offset:22784
	ds_read_b128 v[28:31], v128 offset:22016
	ds_read_b128 v[40:43], v128 offset:22032
	ds_read_b128 v[12:15], v128 offset:21504
	ds_read_b128 v[16:19], v128 offset:21520
	s_waitcnt lgkmcnt(8)
	v_pk_mul_f32 v[66:67], v[34:35], v[22:23]
	v_pk_mul_f32 v[68:69], v[34:35], v[58:59]
	v_pk_fma_f32 v[66:67], v[32:33], v[20:21], v[66:67]
	v_pk_fma_f32 v[68:69], v[32:33], v[56:57], v[68:69]
	v_pk_fma_f32 v[66:67], v[36:37], v[24:25], v[66:67]
	v_pk_fma_f32 v[68:69], v[36:37], v[60:61], v[68:69]
	v_pk_fma_f32 v[66:67], v[38:39], v[26:27], v[66:67]
	v_pk_fma_f32 v[68:69], v[38:39], v[62:63], v[68:69]
	v_add_f32_e32 v66, v66, v67
	v_add_f32_e32 v68, v68, v69
	ds_read_b128 v[20:23], v128 offset:23296
	v_add_f32_dpp v66, v66, v66 quad_perm:[1,0,3,2] row_mask:0xf bank_mask:0xf bound_ctrl:1
	v_add_f32_dpp v68, v68, v68 quad_perm:[1,0,3,2] row_mask:0xf bank_mask:0xf bound_ctrl:1
	ds_read_b128 v[24:27], v128 offset:23312
	v_add_f32_dpp v66, v66, v66 quad_perm:[2,3,0,1] row_mask:0xf bank_mask:0xf bound_ctrl:1
	v_add_f32_dpp v68, v68, v68 quad_perm:[2,3,0,1] row_mask:0xf bank_mask:0xf bound_ctrl:1
	ds_read_b128 v[56:59], v128 offset:22528
	v_add_f32_dpp v66, v66, v66 row_half_mirror row_mask:0xf bank_mask:0xf bound_ctrl:1
	v_add_f32_dpp v68, v68, v68 row_half_mirror row_mask:0xf bank_mask:0xf bound_ctrl:1
	ds_read_b128 v[60:63], v128 offset:22544
	s_waitcnt lgkmcnt(4)
	v_pk_mul_f32 v[70:71], v[28:29], v[66:67] op_sel_hi:[1,0]
	v_pk_mul_f32 v[72:73], v[30:31], v[66:67] op_sel_hi:[1,0]
	v_mov_b32_dpp v69, v68 row_ror:8 row_mask:0xf bank_mask:0xf bound_ctrl:1
	v_pk_mul_f32 v[74:75], v[40:41], v[66:67] op_sel_hi:[1,0]
	v_pk_mul_f32 v[76:77], v[42:43], v[66:67] op_sel_hi:[1,0]
	v_pk_fma_f32 v[70:71], v[44:45], v[64:65], v[70:71] op_sel_hi:[1,0,1]
	v_pk_fma_f32 v[72:73], v[46:47], v[64:65], v[72:73] op_sel_hi:[1,0,1]
	v_pk_fma_f32 v[74:75], v[48:49], v[64:65], v[74:75] op_sel_hi:[1,0,1]
	v_pk_fma_f32 v[76:77], v[50:51], v[64:65], v[76:77] op_sel_hi:[1,0,1]
	v_pk_fma_f32 v[32:33], v[32:33], v[12:13], v[70:71]
	v_pk_fma_f32 v[34:35], v[34:35], v[14:15], v[72:73]
	v_pk_fma_f32 v[36:37], v[36:37], v[16:17], v[74:75]
	v_pk_fma_f32 v[38:39], v[38:39], v[18:19], v[76:77]
	s_and_saveexec_b64 s[18:19], s[12:13]
	v_cvt_pk_bf16_f32 v68, v68, v69
	ds_write_b32 v127, v68 offset:49984
	s_or_b64 exec, exec, s[18:19]
	ds_read_b128 v[44:47], v128 offset:23808
	ds_read_b128 v[48:51], v128 offset:23824
	ds_read_b32 v64, v129 offset:24320
	ds_read_b128 v[28:31], v128 offset:23552
	ds_read_b128 v[40:43], v128 offset:23568
	ds_read_b128 v[12:15], v128 offset:23040
	ds_read_b128 v[16:19], v128 offset:23056
	s_waitcnt lgkmcnt(8)
	v_pk_mul_f32 v[66:67], v[34:35], v[22:23]
	v_pk_mul_f32 v[68:69], v[34:35], v[58:59]
	v_pk_fma_f32 v[66:67], v[32:33], v[20:21], v[66:67]
	v_pk_fma_f32 v[68:69], v[32:33], v[56:57], v[68:69]
	v_pk_fma_f32 v[66:67], v[36:37], v[24:25], v[66:67]
	v_pk_fma_f32 v[68:69], v[36:37], v[60:61], v[68:69]
	v_pk_fma_f32 v[66:67], v[38:39], v[26:27], v[66:67]
	v_pk_fma_f32 v[68:69], v[38:39], v[62:63], v[68:69]
	v_add_f32_e32 v66, v66, v67
	v_add_f32_e32 v68, v68, v69
	ds_read_b128 v[56:59], v128 offset:24064
	v_add_f32_dpp v66, v66, v66 quad_perm:[1,0,3,2] row_mask:0xf bank_mask:0xf bound_ctrl:1
	v_add_f32_dpp v68, v68, v68 quad_perm:[1,0,3,2] row_mask:0xf bank_mask:0xf bound_ctrl:1
	ds_read_b128 v[60:63], v128 offset:24080
	v_add_f32_dpp v66, v66, v66 quad_perm:[2,3,0,1] row_mask:0xf bank_mask:0xf bound_ctrl:1
	v_add_f32_dpp v68, v68, v68 quad_perm:[2,3,0,1] row_mask:0xf bank_mask:0xf bound_ctrl:1
	s_nop 0
	v_add_f32_dpp v66, v66, v66 row_half_mirror row_mask:0xf bank_mask:0xf bound_ctrl:1
	v_add_f32_dpp v68, v68, v68 row_half_mirror row_mask:0xf bank_mask:0xf bound_ctrl:1
	s_waitcnt lgkmcnt(2)
	v_pk_mul_f32 v[70:71], v[28:29], v[66:67] op_sel_hi:[1,0]
	v_pk_mul_f32 v[72:73], v[30:31], v[66:67] op_sel_hi:[1,0]
	v_mov_b32_dpp v69, v68 row_ror:8 row_mask:0xf bank_mask:0xf bound_ctrl:1
	v_pk_mul_f32 v[74:75], v[40:41], v[66:67] op_sel_hi:[1,0]
	v_pk_mul_f32 v[76:77], v[42:43], v[66:67] op_sel_hi:[1,0]
	v_pk_fma_f32 v[70:71], v[44:45], v[64:65], v[70:71] op_sel_hi:[1,0,1]
	v_pk_fma_f32 v[72:73], v[46:47], v[64:65], v[72:73] op_sel_hi:[1,0,1]
	v_pk_fma_f32 v[74:75], v[48:49], v[64:65], v[74:75] op_sel_hi:[1,0,1]
	v_pk_fma_f32 v[76:77], v[50:51], v[64:65], v[76:77] op_sel_hi:[1,0,1]
	v_pk_fma_f32 v[32:33], v[32:33], v[12:13], v[70:71]
	v_pk_fma_f32 v[34:35], v[34:35], v[14:15], v[72:73]
	v_pk_fma_f32 v[36:37], v[36:37], v[16:17], v[74:75]
	v_pk_fma_f32 v[38:39], v[38:39], v[18:19], v[76:77]
	s_and_saveexec_b64 s[18:19], s[12:13]
	v_cvt_pk_bf16_f32 v68, v68, v69
	ds_write_b32 v127, v68 offset:50048
	s_or_b64 exec, exec, s[18:19]
	s_waitcnt lgkmcnt(1)
	v_pk_mul_f32 v[68:69], v[34:35], v[58:59]
	s_nop 0
	v_pk_fma_f32 v[68:69], v[32:33], v[56:57], v[68:69]
	s_nop 0
	v_pk_fma_f32 v[68:69], v[36:37], v[60:61], v[68:69]
	s_nop 0
	v_pk_fma_f32 v[68:69], v[38:39], v[62:63], v[68:69]
	s_nop 0
	v_add_f32_e32 v68, v68, v69
	s_nop 1
	v_add_f32_dpp v68, v68, v68 quad_perm:[1,0,3,2] row_mask:0xf bank_mask:0xf bound_ctrl:1
	s_nop 1
	v_add_f32_dpp v68, v68, v68 quad_perm:[2,3,0,1] row_mask:0xf bank_mask:0xf bound_ctrl:1
	s_nop 1
	v_add_f32_dpp v68, v68, v68 row_half_mirror row_mask:0xf bank_mask:0xf bound_ctrl:1
	s_nop 1
	v_mov_b32_dpp v69, v68 row_ror:8 row_mask:0xf bank_mask:0xf bound_ctrl:1
	s_and_saveexec_b64 s[18:19], s[12:13]
	v_cvt_pk_bf16_f32 v68, v68, v69
	ds_write_b32 v127, v68 offset:50112
	s_or_b64 exec, exec, s[18:19]
	s_and_b64 vcc, exec, s[88:89]
	s_cbranch_vccz .LBB0_481
	s_waitcnt vmcnt(2)
	v_lshlrev_b32_e32 v12, 16, v0
	v_and_or_b32 v20, s51, 16, v105
	v_and_b32_e32 v13, 0xffff0000, v0
	v_lshlrev_b32_e32 v14, 16, v1
	v_and_b32_e32 v15, 0xffff0000, v1
	v_sub_f32_e32 v21, 1.0, v12
	v_lshlrev_b32_e32 v16, 16, v2
	v_and_b32_e32 v17, 0xffff0000, v2
	v_lshlrev_b32_e32 v18, 16, v3
	v_and_b32_e32 v19, 0xffff0000, v3
	v_sub_f32_e32 v22, 1.0, v13
	v_sub_f32_e32 v23, 1.0, v14
	v_sub_f32_e32 v24, 1.0, v15
	v_cndmask_b32_e64 v12, v12, v21, s[4:5]
	v_mad_u32_u24 v21, v20, 6, v101
	v_sub_f32_e32 v25, 1.0, v16
	v_sub_f32_e32 v26, 1.0, v17
	v_sub_f32_e32 v27, 1.0, v18
	v_sub_f32_e32 v28, 1.0, v19
	v_cndmask_b32_e64 v15, v15, v24, s[4:5]
	v_cndmask_b32_e64 v14, v14, v23, s[4:5]
	v_cndmask_b32_e64 v13, v13, v22, s[4:5]
	v_lshl_add_u32 v21, v21, 8, v120
	v_cndmask_b32_e64 v19, v19, v28, s[4:5]
	v_cndmask_b32_e64 v18, v18, v27, s[4:5]
	v_cndmask_b32_e64 v17, v17, v26, s[4:5]
	v_cndmask_b32_e64 v16, v16, v25, s[4:5]
	ds_write_b128 v21, v[12:15]
	ds_write_b128 v21, v[16:19] offset:16
	s_waitcnt vmcnt(1)
	v_lshlrev_b32_e32 v12, 16, v4
	v_and_b32_e32 v13, 0xffff0000, v4
	v_lshlrev_b32_e32 v14, 16, v5
	v_and_b32_e32 v15, 0xffff0000, v5
	v_sub_f32_e32 v21, 1.0, v12
	v_lshlrev_b32_e32 v16, 16, v6
	v_and_b32_e32 v17, 0xffff0000, v6
	v_lshlrev_b32_e32 v18, 16, v7
	v_and_b32_e32 v19, 0xffff0000, v7
	v_sub_f32_e32 v22, 1.0, v13
	v_sub_f32_e32 v23, 1.0, v14
	v_sub_f32_e32 v24, 1.0, v15
	v_cndmask_b32_e64 v12, v12, v21, s[6:7]
	v_mad_u32_u24 v21, v20, 6, v107
	v_sub_f32_e32 v25, 1.0, v16
	v_sub_f32_e32 v26, 1.0, v17
	v_sub_f32_e32 v27, 1.0, v18
	v_sub_f32_e32 v28, 1.0, v19
	v_cndmask_b32_e64 v15, v15, v24, s[6:7]
	v_cndmask_b32_e64 v14, v14, v23, s[6:7]
	v_cndmask_b32_e64 v13, v13, v22, s[6:7]
	v_lshl_add_u32 v21, v21, 8, v120
	v_cndmask_b32_e64 v19, v19, v28, s[6:7]
	v_cndmask_b32_e64 v18, v18, v27, s[6:7]
	v_cndmask_b32_e64 v17, v17, v26, s[6:7]
	v_cndmask_b32_e64 v16, v16, v25, s[6:7]
	ds_write_b128 v21, v[12:15]
	ds_write_b128 v21, v[16:19] offset:16
	s_waitcnt vmcnt(0)
	v_lshlrev_b32_e32 v12, 16, v8
	v_and_b32_e32 v13, 0xffff0000, v8
	v_lshlrev_b32_e32 v14, 16, v9
	v_and_b32_e32 v15, 0xffff0000, v9
	v_lshlrev_b32_e32 v16, 16, v10
	v_and_b32_e32 v17, 0xffff0000, v10
	v_lshlrev_b32_e32 v18, 16, v11
	v_and_b32_e32 v19, 0xffff0000, v11
	v_sub_f32_e32 v21, 1.0, v12
	v_sub_f32_e32 v22, 1.0, v13
	v_sub_f32_e32 v23, 1.0, v14
	v_sub_f32_e32 v24, 1.0, v15
	v_mad_u32_u24 v20, v20, 6, v118
	v_sub_f32_e32 v25, 1.0, v16
	v_sub_f32_e32 v26, 1.0, v17
	v_sub_f32_e32 v27, 1.0, v18
	v_sub_f32_e32 v28, 1.0, v19
	v_cndmask_b32_e64 v15, v15, v24, s[8:9]
	v_cndmask_b32_e64 v14, v14, v23, s[8:9]
	v_cndmask_b32_e64 v13, v13, v22, s[8:9]
	v_cndmask_b32_e64 v12, v12, v21, s[8:9]
	v_lshl_add_u32 v20, v20, 8, v120
	v_cndmask_b32_e64 v19, v19, v28, s[8:9]
	v_cndmask_b32_e64 v18, v18, v27, s[8:9]
	v_cndmask_b32_e64 v17, v17, v26, s[8:9]
	v_cndmask_b32_e64 v16, v16, v25, s[8:9]
	ds_write_b128 v20, v[12:15]
	ds_write_b128 v20, v[16:19] offset:16
	s_branch .LBB0_481
